# K-loop LDS-DMA loads use SGPR base + 32-bit VGPR offset addressing (16 fewer 64-bit VALU adds per iteration)
# baseline (speedup 1.0000x reference)
; #define PG8_STAGE(bufoff, gbase, voff) do { _Pragma("unroll") for (int _i = 0; _i < 2; ++_i) \
;         __builtin_amdgcn_global_load_lds((const unsigned*)((const char*)(gbase) + (voff)[_i]), (LAS unsigned*)(lds + (bufoff) + ldsw + _i * 8192), 16, 0, 0); } while (0)
; #define PG8_LDA(dst, b, h) do { _Pragma("unroll") for (int m = 0; m < 4; ++m) _Pragma("unroll") for (int k = 0; k < 2; ++k) dst[m][k] = *(const LAS bf16x8*)(lds + PG8_SA(b, h) + aoff + m * 2048 + k * 1024); } while (0)
; #define PG8_LDB(dst, b, h) do { _Pragma("unroll") for (int n = 0; n < 2; ++n) _Pragma("unroll") for (int k = 0; k < 2; ++k) dst[n][k] = *(const LAS bf16x8*)(lds + PG8_SB(b, h) + boff + n * 2048 + k * 1024); } while (0)
; #define PG8_MMA(ai, bj, At, Bt) do { __builtin_amdgcn_s_setprio(1); _Pragma("unroll") for (int m = 0; m < 4; ++m) _Pragma("unroll") for (int n = 0; n < 2; ++n) _Pragma("unroll") for (int k = 0; k < 2; ++k) \
;         acc[ai][bj][m][n] = __builtin_amdgcn_mfma_f32_16x16x32_bf16(Bt[n][k], At[m][k], acc[ai][bj][m][n], 0, 0, 0); __builtin_amdgcn_s_setprio(0); } while (0)
; #define PG8_WAIT_V(n) asm volatile("s_waitcnt vmcnt(" #n ")" ::: "memory")
; #define PG8_WAIT_L(n) asm volatile("s_waitcnt lgkmcnt(" #n ")" ::: "memory")
; #define PG8_BAR __builtin_amdgcn_s_barrier()
; #define PG8_SCHED __builtin_amdgcn_sched_barrier(0)
; template <class Epi, class Sched, bool ALIGN_EPI = false, bool SP2 = false>
; __device__ __forceinline__ void gemm_phase(LAS unsigned char* lds, const Gemm g, const Sched& S, const Epi& E) {
;     ...
;             PG8_LDB(B0, 0, 0); PG8_LDB(B1, 0, 1); PG8_SCHED; PG8_LDA(At, 0, 0); PG8_STAGE(PG8_SA(1, 1), a1 + hstep, voffA);
;             PG8_WAIT_V(8); PG8_WAIT_L(0); PG8_BAR; PG8_MMA(0, 0, At, B0); PG8_MMA(0, 1, At, B1); PG8_BAR; PG8_SCHED;
;             PG8_LDA(At, 0, 1); PG8_STAGE(PG8_SB(0, 0), b2, voffB); PG8_STAGE(PG8_SB(0, 1), b2 + hstep, voffB); PG8_STAGE(PG8_SA(0, 0), a2, voffA);
;             PG8_WAIT_V(8); PG8_WAIT_L(0); PG8_BAR; PG8_MMA(1, 0, At, B0); PG8_MMA(1, 1, At, B1); PG8_BAR; PG8_SCHED;
.LBB0_260:
	s_add_u32 s12, s10, 0xfff00080
	s_addc_u32 s13, s11, -1
	s_add_i32 s44, 0, 0x10000
	s_cmp_eq_u32 s42, 60
	s_cselect_b32 s15, s2, s13
	s_cselect_b32 s14, s3, s12
	v_add_u32_e32 v146, s44, v149
	s_cselect_b32 s13, s17, s41
	s_cselect_b32 s12, s23, s25
	s_add_i32 s48, 0, 0x14000
	ds_read_b128 v[142:145], v146
	ds_read_b128 v[156:159], v146 offset:1024
	ds_read_b128 v[160:163], v146 offset:2048
	ds_read_b128 v[164:167], v146 offset:3072
	v_add_u32_e32 v146, s48, v149
	ds_read_b128 v[168:171], v146
	ds_read_b128 v[172:175], v146 offset:1024
	ds_read_b128 v[176:179], v146 offset:2048
	ds_read_b128 v[180:183], v146 offset:3072
	s_add_i32 m0, s34, 0xc000
	ds_read_b128 v[184:187], v155
	ds_read_b128 v[188:191], v155 offset:1024
	ds_read_b128 v[198:201], v155 offset:2048
	ds_read_b128 v[202:205], v155 offset:3072
	ds_read_b128 v[206:209], v155 offset:4096
	ds_read_b128 v[210:213], v155 offset:5120
	ds_read_b128 v[214:217], v155 offset:6144
	ds_read_b128 v[228:231], v155 offset:7168
	global_load_lds_dwordx4 v138, s[10:11]
	s_add_i32 m0, s34, 0xe000
	s_nop 0
	global_load_lds_dwordx4 v140, s[10:11]
	s_waitcnt vmcnt(8)
	s_waitcnt lgkmcnt(0)
	s_barrier
	s_setprio 1
	s_waitcnt lgkmcnt(0)
	v_mfma_f32_16x16x32_bf16 v[124:127], v[142:145], v[184:187], v[124:127]
	v_mfma_f32_16x16x32_bf16 v[120:123], v[160:163], v[184:187], v[120:123]
	v_mfma_f32_16x16x32_bf16 v[108:111], v[142:145], v[198:201], v[108:111]
	v_mfma_f32_16x16x32_bf16 v[104:107], v[160:163], v[198:201], v[104:107]
	v_mfma_f32_16x16x32_bf16 v[92:95], v[142:145], v[206:209], v[92:95]
	v_mfma_f32_16x16x32_bf16 v[88:91], v[160:163], v[206:209], v[88:91]
	v_mfma_f32_16x16x32_bf16 v[76:79], v[142:145], v[214:217], v[76:79]
	v_mfma_f32_16x16x32_bf16 v[72:75], v[160:163], v[214:217], v[72:75]
	v_mfma_f32_16x16x32_bf16 v[124:127], v[156:159], v[188:191], v[124:127]
	v_mfma_f32_16x16x32_bf16 v[120:123], v[164:167], v[188:191], v[120:123]
	v_mfma_f32_16x16x32_bf16 v[108:111], v[156:159], v[202:205], v[108:111]
	v_mfma_f32_16x16x32_bf16 v[104:107], v[164:167], v[202:205], v[104:107]
	v_mfma_f32_16x16x32_bf16 v[92:95], v[156:159], v[210:213], v[92:95]
	v_mfma_f32_16x16x32_bf16 v[88:91], v[164:167], v[210:213], v[88:91]
	v_mfma_f32_16x16x32_bf16 v[76:79], v[156:159], v[228:231], v[76:79]
	v_mfma_f32_16x16x32_bf16 v[72:75], v[164:167], v[228:231], v[72:75]
	s_setprio 0
	s_setprio 1
	v_mfma_f32_16x16x32_bf16 v[116:119], v[168:171], v[184:187], v[116:119]
	v_mfma_f32_16x16x32_bf16 v[112:115], v[176:179], v[184:187], v[112:115]
	v_mfma_f32_16x16x32_bf16 v[100:103], v[168:171], v[198:201], v[100:103]
	v_mfma_f32_16x16x32_bf16 v[96:99], v[176:179], v[198:201], v[96:99]
	v_mfma_f32_16x16x32_bf16 v[84:87], v[168:171], v[206:209], v[84:87]
	v_mfma_f32_16x16x32_bf16 v[80:83], v[176:179], v[206:209], v[80:83]
	v_mfma_f32_16x16x32_bf16 v[68:71], v[168:171], v[214:217], v[68:71]
	v_mfma_f32_16x16x32_bf16 v[64:67], v[176:179], v[214:217], v[64:67]
	v_mfma_f32_16x16x32_bf16 v[116:119], v[172:175], v[188:191], v[116:119]
	v_mfma_f32_16x16x32_bf16 v[112:115], v[180:183], v[188:191], v[112:115]
	v_mfma_f32_16x16x32_bf16 v[100:103], v[172:175], v[202:205], v[100:103]
	v_mfma_f32_16x16x32_bf16 v[96:99], v[180:183], v[202:205], v[96:99]
	v_mfma_f32_16x16x32_bf16 v[84:87], v[172:175], v[210:213], v[84:87]
	v_mfma_f32_16x16x32_bf16 v[80:83], v[180:183], v[210:213], v[80:83]
	v_mfma_f32_16x16x32_bf16 v[68:71], v[172:175], v[228:231], v[68:71]
	v_mfma_f32_16x16x32_bf16 v[64:67], v[180:183], v[228:231], v[64:67]
	s_setprio 0
	s_barrier
	s_add_u32 s98, s12, 0x80
	s_addc_u32 s99, s13, 0
	s_add_u32 s100, s14, 0x80
	s_addc_u32 s101, s15, 0
	s_add_i32 s44, s44, s7
	s_mov_b32 m0, s44
	ds_read_b128 v[184:187], v155 offset:16384
	ds_read_b128 v[188:191], v155 offset:17408
	ds_read_b128 v[198:201], v155 offset:18432
	ds_read_b128 v[202:205], v155 offset:19456
	ds_read_b128 v[206:209], v155 offset:20480
	ds_read_b128 v[210:213], v155 offset:21504
	ds_read_b128 v[214:217], v155 offset:22528
	ds_read_b128 v[228:231], v155 offset:23552
	global_load_lds_dwordx4 v196, s[12:13]
	s_add_i32 m0, s44, 0x2000
	s_add_u32 s46, s12, 0x100000
	s_addc_u32 s47, s13, 0
	s_add_i32 s44, s48, s7
	global_load_lds_dwordx4 v128, s[12:13]
	s_mov_b32 m0, s44
	s_nop 0
	global_load_lds_dwordx4 v196, s[46:47]
	s_add_i32 m0, s44, 0x2000
	s_nop 0
	global_load_lds_dwordx4 v128, s[46:47]
	s_mov_b32 m0, s34
	s_nop 0
	global_load_lds_dwordx4 v132, s[14:15]
	s_mov_b32 m0, s35
	s_nop 0
	global_load_lds_dwordx4 v130, s[14:15]
	s_waitcnt vmcnt(8)
	s_waitcnt lgkmcnt(0)
	s_barrier
; #define PG8_STAGE(bufoff, gbase, voff) do { _Pragma("unroll") for (int _i = 0; _i < 2; ++_i) \
;         __builtin_amdgcn_global_load_lds((const unsigned*)((const char*)(gbase) + (voff)[_i]), (LAS unsigned*)(lds + (bufoff) + ldsw + _i * 8192), 16, 0, 0); } while (0)
; #define PG8_LDA(dst, b, h) do { _Pragma("unroll") for (int m = 0; m < 4; ++m) _Pragma("unroll") for (int k = 0; k < 2; ++k) dst[m][k] = *(const LAS bf16x8*)(lds + PG8_SA(b, h) + aoff + m * 2048 + k * 1024); } while (0)
; #define PG8_LDB(dst, b, h) do { _Pragma("unroll") for (int n = 0; n < 2; ++n) _Pragma("unroll") for (int k = 0; k < 2; ++k) dst[n][k] = *(const LAS bf16x8*)(lds + PG8_SB(b, h) + boff + n * 2048 + k * 1024); } while (0)
; #define PG8_MMA(ai, bj, At, Bt) do { __builtin_amdgcn_s_setprio(1); _Pragma("unroll") for (int m = 0; m < 4; ++m) _Pragma("unroll") for (int n = 0; n < 2; ++n) _Pragma("unroll") for (int k = 0; k < 2; ++k) \
;         acc[ai][bj][m][n] = __builtin_amdgcn_mfma_f32_16x16x32_bf16(Bt[n][k], At[m][k], acc[ai][bj][m][n], 0, 0, 0); __builtin_amdgcn_s_setprio(0); } while (0)
; #define PG8_WAIT_V(n) asm volatile("s_waitcnt vmcnt(" #n ")" ::: "memory")
; #define PG8_WAIT_L(n) asm volatile("s_waitcnt lgkmcnt(" #n ")" ::: "memory")
; #define PG8_BAR __builtin_amdgcn_s_barrier()
; #define PG8_SCHED __builtin_amdgcn_sched_barrier(0)
; template <class Epi, class Sched, bool ALIGN_EPI = false, bool SP2 = false>
; __device__ __forceinline__ void gemm_phase(LAS unsigned char* lds, const Gemm g, const Sched& S, const Epi& E) {
;     ...
;             PG8_WAIT_V(8); PG8_WAIT_L(0); PG8_BAR; PG8_MMA(0, 0, At, B0); PG8_MMA(0, 1, At, B1); PG8_BAR; PG8_SCHED;
;             PG8_LDA(At, 0, 1); PG8_STAGE(PG8_SB(0, 0), b2, voffB); PG8_STAGE(PG8_SB(0, 1), b2 + hstep, voffB); PG8_STAGE(PG8_SA(0, 0), a2, voffA);
;             PG8_WAIT_V(8); PG8_WAIT_L(0); PG8_BAR; PG8_MMA(1, 0, At, B0); PG8_MMA(1, 1, At, B1); PG8_BAR; PG8_SCHED;
;             PG8_LDB(B0, 1, 0); PG8_LDB(B1, 1, 1); PG8_SCHED; PG8_LDA(At, 1, 0); PG8_STAGE(PG8_SA(0, 1), a2 + hstep, voffA);
;             PG8_WAIT_V(8); PG8_WAIT_L(0); PG8_BAR; PG8_MMA(0, 0, At, B0); PG8_MMA(0, 1, At, B1); PG8_BAR; PG8_SCHED;
	s_setprio 1
	s_waitcnt lgkmcnt(0)
	v_mfma_f32_16x16x32_bf16 v[60:63], v[142:145], v[184:187], v[60:63]
	v_mfma_f32_16x16x32_bf16 v[56:59], v[160:163], v[184:187], v[56:59]
	v_mfma_f32_16x16x32_bf16 v[44:47], v[142:145], v[198:201], v[44:47]
	v_mfma_f32_16x16x32_bf16 v[40:43], v[160:163], v[198:201], v[40:43]
	v_mfma_f32_16x16x32_bf16 v[28:31], v[142:145], v[206:209], v[28:31]
	v_mfma_f32_16x16x32_bf16 v[24:27], v[160:163], v[206:209], v[24:27]
	v_mfma_f32_16x16x32_bf16 v[12:15], v[142:145], v[214:217], v[12:15]
	v_mfma_f32_16x16x32_bf16 v[8:11], v[160:163], v[214:217], v[8:11]
	v_mfma_f32_16x16x32_bf16 v[60:63], v[156:159], v[188:191], v[60:63]
	v_mfma_f32_16x16x32_bf16 v[56:59], v[164:167], v[188:191], v[56:59]
	v_mfma_f32_16x16x32_bf16 v[44:47], v[156:159], v[202:205], v[44:47]
	v_mfma_f32_16x16x32_bf16 v[40:43], v[164:167], v[202:205], v[40:43]
	v_mfma_f32_16x16x32_bf16 v[28:31], v[156:159], v[210:213], v[28:31]
	v_mfma_f32_16x16x32_bf16 v[24:27], v[164:167], v[210:213], v[24:27]
	v_mfma_f32_16x16x32_bf16 v[12:15], v[156:159], v[228:231], v[12:15]
	v_mfma_f32_16x16x32_bf16 v[8:11], v[164:167], v[228:231], v[8:11]
	s_setprio 0
	s_setprio 1
	v_mfma_f32_16x16x32_bf16 v[52:55], v[168:171], v[184:187], v[52:55]
	v_mfma_f32_16x16x32_bf16 v[48:51], v[176:179], v[184:187], v[48:51]
	v_mfma_f32_16x16x32_bf16 v[36:39], v[168:171], v[198:201], v[36:39]
	v_mfma_f32_16x16x32_bf16 v[32:35], v[176:179], v[198:201], v[32:35]
	v_mfma_f32_16x16x32_bf16 v[20:23], v[168:171], v[206:209], v[20:23]
	v_mfma_f32_16x16x32_bf16 v[16:19], v[176:179], v[206:209], v[16:19]
	v_mfma_f32_16x16x32_bf16 v[4:7], v[168:171], v[214:217], v[4:7]
	v_mfma_f32_16x16x32_bf16 v[0:3], v[176:179], v[214:217], v[0:3]
	v_mfma_f32_16x16x32_bf16 v[52:55], v[172:175], v[188:191], v[52:55]
	v_mfma_f32_16x16x32_bf16 v[48:51], v[180:183], v[188:191], v[48:51]
	v_mfma_f32_16x16x32_bf16 v[36:39], v[172:175], v[202:205], v[36:39]
	v_mfma_f32_16x16x32_bf16 v[32:35], v[180:183], v[202:205], v[32:35]
	v_mfma_f32_16x16x32_bf16 v[20:23], v[172:175], v[210:213], v[20:23]
	v_mfma_f32_16x16x32_bf16 v[16:19], v[180:183], v[210:213], v[16:19]
	v_mfma_f32_16x16x32_bf16 v[4:7], v[172:175], v[228:231], v[4:7]
	v_mfma_f32_16x16x32_bf16 v[0:3], v[180:183], v[228:231], v[0:3]
	s_setprio 0
	s_barrier
	s_add_i32 s44, 0, 0x18000
	s_add_i32 s46, 0, 0x1c000
	v_add_u32_e32 v164, s44, v149
	v_add_u32_e32 v180, s46, v149
	ds_read_b128 v[142:145], v164
	ds_read_b128 v[156:159], v164 offset:1024
	ds_read_b128 v[160:163], v164 offset:2048
	ds_read_b128 v[164:167], v164 offset:3072
	ds_read_b128 v[168:171], v180
	ds_read_b128 v[172:175], v180 offset:1024
	ds_read_b128 v[176:179], v180 offset:2048
	ds_read_b128 v[180:183], v180 offset:3072
	s_add_u32 s14, s14, 0x100000
	s_addc_u32 s15, s15, 0
	s_mov_b32 m0, s36
	ds_read_b128 v[184:187], v155 offset:32768
	ds_read_b128 v[188:191], v155 offset:33792
	ds_read_b128 v[198:201], v155 offset:34816
	ds_read_b128 v[202:205], v155 offset:35840
	ds_read_b128 v[206:209], v155 offset:36864
	ds_read_b128 v[210:213], v155 offset:37888
	ds_read_b128 v[214:217], v155 offset:38912
	ds_read_b128 v[228:231], v155 offset:39936
	global_load_lds_dwordx4 v132, s[14:15]
	s_mov_b32 m0, s37
	s_nop 0
	global_load_lds_dwordx4 v130, s[14:15]
	s_waitcnt vmcnt(8)
	s_waitcnt lgkmcnt(0)
	s_barrier
	s_setprio 1
	s_waitcnt lgkmcnt(0)
	v_mfma_f32_16x16x32_bf16 v[124:127], v[142:145], v[184:187], v[124:127]
	v_mfma_f32_16x16x32_bf16 v[120:123], v[160:163], v[184:187], v[120:123]
	v_mfma_f32_16x16x32_bf16 v[108:111], v[142:145], v[198:201], v[108:111]
	v_mfma_f32_16x16x32_bf16 v[104:107], v[160:163], v[198:201], v[104:107]
	v_mfma_f32_16x16x32_bf16 v[92:95], v[142:145], v[206:209], v[92:95]
	v_mfma_f32_16x16x32_bf16 v[88:91], v[160:163], v[206:209], v[88:91]
	v_mfma_f32_16x16x32_bf16 v[76:79], v[142:145], v[214:217], v[76:79]
	v_mfma_f32_16x16x32_bf16 v[72:75], v[160:163], v[214:217], v[72:75]
	v_mfma_f32_16x16x32_bf16 v[124:127], v[156:159], v[188:191], v[124:127]
	v_mfma_f32_16x16x32_bf16 v[120:123], v[164:167], v[188:191], v[120:123]
	v_mfma_f32_16x16x32_bf16 v[108:111], v[156:159], v[202:205], v[108:111]
	v_mfma_f32_16x16x32_bf16 v[104:107], v[164:167], v[202:205], v[104:107]
	v_mfma_f32_16x16x32_bf16 v[92:95], v[156:159], v[210:213], v[92:95]
	v_mfma_f32_16x16x32_bf16 v[88:91], v[164:167], v[210:213], v[88:91]
	v_mfma_f32_16x16x32_bf16 v[76:79], v[156:159], v[228:231], v[76:79]
	v_mfma_f32_16x16x32_bf16 v[72:75], v[164:167], v[228:231], v[72:75]
	s_setprio 0
	s_setprio 1
	v_mfma_f32_16x16x32_bf16 v[116:119], v[168:171], v[184:187], v[116:119]
	v_mfma_f32_16x16x32_bf16 v[112:115], v[176:179], v[184:187], v[112:115]
	v_mfma_f32_16x16x32_bf16 v[100:103], v[168:171], v[198:201], v[100:103]
	v_mfma_f32_16x16x32_bf16 v[96:99], v[176:179], v[198:201], v[96:99]
	v_mfma_f32_16x16x32_bf16 v[84:87], v[168:171], v[206:209], v[84:87]
	v_mfma_f32_16x16x32_bf16 v[80:83], v[176:179], v[206:209], v[80:83]
	v_mfma_f32_16x16x32_bf16 v[68:71], v[168:171], v[214:217], v[68:71]
	v_mfma_f32_16x16x32_bf16 v[64:67], v[176:179], v[214:217], v[64:67]
	v_mfma_f32_16x16x32_bf16 v[116:119], v[172:175], v[188:191], v[116:119]
	v_mfma_f32_16x16x32_bf16 v[112:115], v[180:183], v[188:191], v[112:115]
	v_mfma_f32_16x16x32_bf16 v[100:103], v[172:175], v[202:205], v[100:103]
	v_mfma_f32_16x16x32_bf16 v[96:99], v[180:183], v[202:205], v[96:99]
	v_mfma_f32_16x16x32_bf16 v[84:87], v[172:175], v[210:213], v[84:87]
	v_mfma_f32_16x16x32_bf16 v[80:83], v[180:183], v[210:213], v[80:83]
	v_mfma_f32_16x16x32_bf16 v[68:71], v[172:175], v[228:231], v[68:71]
	v_mfma_f32_16x16x32_bf16 v[64:67], v[180:183], v[228:231], v[64:67]
	s_setprio 0
	s_barrier
; #define PG8_STAGE(bufoff, gbase, voff) do { _Pragma("unroll") for (int _i = 0; _i < 2; ++_i) \
;         __builtin_amdgcn_global_load_lds((const unsigned*)((const char*)(gbase) + (voff)[_i]), (LAS unsigned*)(lds + (bufoff) + ldsw + _i * 8192), 16, 0, 0); } while (0)
; #define PG8_LDA(dst, b, h) do { _Pragma("unroll") for (int m = 0; m < 4; ++m) _Pragma("unroll") for (int k = 0; k < 2; ++k) dst[m][k] = *(const LAS bf16x8*)(lds + PG8_SA(b, h) + aoff + m * 2048 + k * 1024); } while (0)
; #define PG8_MMA(ai, bj, At, Bt) do { __builtin_amdgcn_s_setprio(1); _Pragma("unroll") for (int m = 0; m < 4; ++m) _Pragma("unroll") for (int n = 0; n < 2; ++n) _Pragma("unroll") for (int k = 0; k < 2; ++k) \
;         acc[ai][bj][m][n] = __builtin_amdgcn_mfma_f32_16x16x32_bf16(Bt[n][k], At[m][k], acc[ai][bj][m][n], 0, 0, 0); __builtin_amdgcn_s_setprio(0); } while (0)
; #define PG8_WAIT_V(n) asm volatile("s_waitcnt vmcnt(" #n ")" ::: "memory")
; #define PG8_WAIT_L(n) asm volatile("s_waitcnt lgkmcnt(" #n ")" ::: "memory")
; #define PG8_BAR __builtin_amdgcn_s_barrier()
; #define PG8_SCHED __builtin_amdgcn_sched_barrier(0)
; template <class Epi, class Sched, bool ALIGN_EPI = false, bool SP2 = false>
; __device__ __forceinline__ void gemm_phase(LAS unsigned char* lds, const Gemm g, const Sched& S, const Epi& E) {
;     ...
;             PG8_WAIT_V(8); PG8_WAIT_L(0); PG8_BAR; PG8_MMA(0, 0, At, B0); PG8_MMA(0, 1, At, B1); PG8_BAR; PG8_SCHED;
;             PG8_LDA(At, 1, 1); PG8_STAGE(PG8_SB(1, 0), b3, voffB); PG8_STAGE(PG8_SB(1, 1), b3 + hstep, voffB); PG8_STAGE(PG8_SA(1, 0), a3, voffA);
;             PG8_WAIT_V(8); PG8_WAIT_L(0); PG8_BAR; PG8_MMA(1, 0, At, B0); PG8_MMA(1, 1, At, B1); PG8_BAR; PG8_SCHED;
	s_add_i32 s14, s44, s7
	s_mov_b32 m0, s14
	ds_read_b128 v[184:187], v155 offset:49152
	ds_read_b128 v[188:191], v155 offset:50176
	ds_read_b128 v[198:201], v155 offset:51200
	ds_read_b128 v[202:205], v155 offset:52224
	ds_read_b128 v[206:209], v155 offset:53248
	ds_read_b128 v[210:213], v155 offset:54272
	ds_read_b128 v[214:217], v155 offset:55296
	ds_read_b128 v[228:231], v155 offset:56320
	global_load_lds_dwordx4 v196, s[98:99]
	s_add_i32 m0, s14, 0x2000
	s_add_u32 s12, s12, 0x100080
	s_addc_u32 s13, s13, 0
	s_add_i32 s14, s46, s7
	global_load_lds_dwordx4 v128, s[98:99]
	s_mov_b32 m0, s14
	s_nop 0
	global_load_lds_dwordx4 v196, s[12:13]
	s_add_i32 m0, s14, 0x2000
	s_nop 0
	global_load_lds_dwordx4 v128, s[12:13]
	s_mov_b32 m0, s38
	s_nop 0
	global_load_lds_dwordx4 v132, s[100:101]
	s_mov_b32 m0, s39
	s_nop 0
	global_load_lds_dwordx4 v130, s[100:101]
	s_waitcnt vmcnt(8)
	s_waitcnt lgkmcnt(0)
	s_barrier
	s_setprio 1
	s_waitcnt lgkmcnt(0)
	v_mfma_f32_16x16x32_bf16 v[60:63], v[142:145], v[184:187], v[60:63]
	v_mfma_f32_16x16x32_bf16 v[56:59], v[160:163], v[184:187], v[56:59]
	v_mfma_f32_16x16x32_bf16 v[44:47], v[142:145], v[198:201], v[44:47]
	v_mfma_f32_16x16x32_bf16 v[40:43], v[160:163], v[198:201], v[40:43]
	v_mfma_f32_16x16x32_bf16 v[28:31], v[142:145], v[206:209], v[28:31]
	v_mfma_f32_16x16x32_bf16 v[24:27], v[160:163], v[206:209], v[24:27]
	v_mfma_f32_16x16x32_bf16 v[12:15], v[142:145], v[214:217], v[12:15]
	v_mfma_f32_16x16x32_bf16 v[8:11], v[160:163], v[214:217], v[8:11]
	v_mfma_f32_16x16x32_bf16 v[60:63], v[156:159], v[188:191], v[60:63]
	v_mfma_f32_16x16x32_bf16 v[56:59], v[164:167], v[188:191], v[56:59]
	v_mfma_f32_16x16x32_bf16 v[44:47], v[156:159], v[202:205], v[44:47]
	v_mfma_f32_16x16x32_bf16 v[40:43], v[164:167], v[202:205], v[40:43]
	v_mfma_f32_16x16x32_bf16 v[28:31], v[156:159], v[210:213], v[28:31]
	v_mfma_f32_16x16x32_bf16 v[24:27], v[164:167], v[210:213], v[24:27]
	v_mfma_f32_16x16x32_bf16 v[12:15], v[156:159], v[228:231], v[12:15]
	v_mfma_f32_16x16x32_bf16 v[8:11], v[164:167], v[228:231], v[8:11]
	s_setprio 0
	s_setprio 1
	v_mfma_f32_16x16x32_bf16 v[52:55], v[168:171], v[184:187], v[52:55]
	v_mfma_f32_16x16x32_bf16 v[48:51], v[176:179], v[184:187], v[48:51]
	v_mfma_f32_16x16x32_bf16 v[36:39], v[168:171], v[198:201], v[36:39]
	v_mfma_f32_16x16x32_bf16 v[32:35], v[176:179], v[198:201], v[32:35]
	v_mfma_f32_16x16x32_bf16 v[20:23], v[168:171], v[206:209], v[20:23]
	v_mfma_f32_16x16x32_bf16 v[16:19], v[176:179], v[206:209], v[16:19]
	v_mfma_f32_16x16x32_bf16 v[4:7], v[168:171], v[214:217], v[4:7]
	v_mfma_f32_16x16x32_bf16 v[0:3], v[176:179], v[214:217], v[0:3]
	v_mfma_f32_16x16x32_bf16 v[52:55], v[172:175], v[188:191], v[52:55]
	v_mfma_f32_16x16x32_bf16 v[48:51], v[180:183], v[188:191], v[48:51]
	v_mfma_f32_16x16x32_bf16 v[36:39], v[172:175], v[202:205], v[36:39]
	v_mfma_f32_16x16x32_bf16 v[32:35], v[180:183], v[202:205], v[32:35]
	v_mfma_f32_16x16x32_bf16 v[20:23], v[172:175], v[210:213], v[20:23]
	v_mfma_f32_16x16x32_bf16 v[16:19], v[180:183], v[210:213], v[16:19]
	v_mfma_f32_16x16x32_bf16 v[4:7], v[172:175], v[228:231], v[4:7]
	v_mfma_f32_16x16x32_bf16 v[0:3], v[180:183], v[228:231], v[0:3]
	s_setprio 0
	s_barrier
	s_add_i32 s42, s42, 2
	s_add_u32 s10, s10, 0x100
	s_addc_u32 s11, s11, 0
	s_add_u32 s25, s25, 0x100
	s_addc_u32 s41, s41, 0
	s_cmp_gt_u32 s42, 61
	s_cbranch_scc0 .LBB0_260
	s_and_b64 vcc, exec, s[20:21]
	s_cbranch_vccz .LBB0_263
	s_barrier

; #define PG8_STAGE(bufoff, gbase, voff) do { _Pragma("unroll") for (int _i = 0; _i < 2; ++_i) \
;         __builtin_amdgcn_global_load_lds((const unsigned*)((const char*)(gbase) + (voff)[_i]), (LAS unsigned*)(lds + (bufoff) + ldsw + _i * 8192), 16, 0, 0); } while (0)
; #define PG8_LDA(dst, b, h) do { _Pragma("unroll") for (int m = 0; m < 4; ++m) _Pragma("unroll") for (int k = 0; k < 2; ++k) dst[m][k] = *(const LAS bf16x8*)(lds + PG8_SA(b, h) + aoff + m * 2048 + k * 1024); } while (0)
; #define PG8_LDB(dst, b, h) do { _Pragma("unroll") for (int n = 0; n < 2; ++n) _Pragma("unroll") for (int k = 0; k < 2; ++k) dst[n][k] = *(const LAS bf16x8*)(lds + PG8_SB(b, h) + boff + n * 2048 + k * 1024); } while (0)
; #define PG8_MMA(ai, bj, At, Bt) do { __builtin_amdgcn_s_setprio(1); _Pragma("unroll") for (int m = 0; m < 4; ++m) _Pragma("unroll") for (int n = 0; n < 2; ++n) _Pragma("unroll") for (int k = 0; k < 2; ++k) \
;         acc[ai][bj][m][n] = __builtin_amdgcn_mfma_f32_16x16x32_bf16(Bt[n][k], At[m][k], acc[ai][bj][m][n], 0, 0, 0); __builtin_amdgcn_s_setprio(0); } while (0)
; #define PG8_WAIT_V(n) asm volatile("s_waitcnt vmcnt(" #n ")" ::: "memory")
; #define PG8_WAIT_L(n) asm volatile("s_waitcnt lgkmcnt(" #n ")" ::: "memory")
; #define PG8_BAR __builtin_amdgcn_s_barrier()
; #define PG8_SCHED __builtin_amdgcn_sched_barrier(0)
; template <class Epi, class Sched, bool ALIGN_EPI = false, bool SP2 = false>
; __device__ __forceinline__ void gemm_phase(LAS unsigned char* lds, const Gemm g, const Sched& S, const Epi& E) {
;     ...
;             PG8_LDB(B0, 0, 0); PG8_LDB(B1, 0, 1); PG8_SCHED; PG8_LDA(At, 0, 0); PG8_STAGE(PG8_SA(1, 1), a1 + hstep, voffA);
;             PG8_WAIT_V(8); PG8_WAIT_L(0); PG8_BAR; PG8_MMA(0, 0, At, B0); PG8_MMA(0, 1, At, B1); PG8_BAR; PG8_SCHED;
;             PG8_LDA(At, 0, 1); PG8_STAGE(PG8_SB(0, 0), b2, voffB); PG8_STAGE(PG8_SB(0, 1), b2 + hstep, voffB); PG8_STAGE(PG8_SA(0, 0), a2, voffA);
;             PG8_WAIT_V(8); PG8_WAIT_L(0); PG8_BAR; PG8_MMA(1, 0, At, B0); PG8_MMA(1, 1, At, B1); PG8_BAR; PG8_SCHED;
.LBB0_424:
	s_add_u32 s12, s10, 0xfff00080
	s_addc_u32 s13, s11, -1
	s_add_i32 s48, 0, 0x10000
	s_cmp_eq_u32 s42, 60
	s_cselect_b32 s15, s2, s13
	s_cselect_b32 s14, s3, s12
	v_add_u32_e32 v146, s48, v149
	s_cselect_b32 s13, s17, s41
	s_cselect_b32 s12, s23, s25
	s_add_i32 s90, 0, 0x14000
	ds_read_b128 v[142:145], v146
	ds_read_b128 v[156:159], v146 offset:1024
	ds_read_b128 v[160:163], v146 offset:2048
	ds_read_b128 v[164:167], v146 offset:3072
	v_add_u32_e32 v146, s90, v149
	ds_read_b128 v[168:171], v146
	ds_read_b128 v[172:175], v146 offset:1024
	ds_read_b128 v[176:179], v146 offset:2048
	ds_read_b128 v[180:183], v146 offset:3072
	s_add_i32 m0, s34, 0xc000
	ds_read_b128 v[184:187], v155
	ds_read_b128 v[188:191], v155 offset:1024
	ds_read_b128 v[198:201], v155 offset:2048
	ds_read_b128 v[202:205], v155 offset:3072
	ds_read_b128 v[206:209], v155 offset:4096
	ds_read_b128 v[210:213], v155 offset:5120
	ds_read_b128 v[214:217], v155 offset:6144
	ds_read_b128 v[228:231], v155 offset:7168
	global_load_lds_dwordx4 v138, s[10:11]
	s_add_i32 m0, s34, 0xe000
	s_nop 0
	global_load_lds_dwordx4 v140, s[10:11]
	s_waitcnt vmcnt(8)
	s_waitcnt lgkmcnt(0)
	s_barrier
	s_setprio 1
	s_waitcnt lgkmcnt(0)
	v_mfma_f32_16x16x32_bf16 v[124:127], v[142:145], v[184:187], v[124:127]
	v_mfma_f32_16x16x32_bf16 v[120:123], v[160:163], v[184:187], v[120:123]
	v_mfma_f32_16x16x32_bf16 v[108:111], v[142:145], v[198:201], v[108:111]
	v_mfma_f32_16x16x32_bf16 v[104:107], v[160:163], v[198:201], v[104:107]
	v_mfma_f32_16x16x32_bf16 v[92:95], v[142:145], v[206:209], v[92:95]
	v_mfma_f32_16x16x32_bf16 v[88:91], v[160:163], v[206:209], v[88:91]
	v_mfma_f32_16x16x32_bf16 v[76:79], v[142:145], v[214:217], v[76:79]
	v_mfma_f32_16x16x32_bf16 v[72:75], v[160:163], v[214:217], v[72:75]
	v_mfma_f32_16x16x32_bf16 v[124:127], v[156:159], v[188:191], v[124:127]
	v_mfma_f32_16x16x32_bf16 v[120:123], v[164:167], v[188:191], v[120:123]
	v_mfma_f32_16x16x32_bf16 v[108:111], v[156:159], v[202:205], v[108:111]
	v_mfma_f32_16x16x32_bf16 v[104:107], v[164:167], v[202:205], v[104:107]
	v_mfma_f32_16x16x32_bf16 v[92:95], v[156:159], v[210:213], v[92:95]
	v_mfma_f32_16x16x32_bf16 v[88:91], v[164:167], v[210:213], v[88:91]
	v_mfma_f32_16x16x32_bf16 v[76:79], v[156:159], v[228:231], v[76:79]
	v_mfma_f32_16x16x32_bf16 v[72:75], v[164:167], v[228:231], v[72:75]
	s_setprio 0
	s_setprio 1
	v_mfma_f32_16x16x32_bf16 v[116:119], v[168:171], v[184:187], v[116:119]
	v_mfma_f32_16x16x32_bf16 v[112:115], v[176:179], v[184:187], v[112:115]
	v_mfma_f32_16x16x32_bf16 v[100:103], v[168:171], v[198:201], v[100:103]
	v_mfma_f32_16x16x32_bf16 v[96:99], v[176:179], v[198:201], v[96:99]
	v_mfma_f32_16x16x32_bf16 v[84:87], v[168:171], v[206:209], v[84:87]
	v_mfma_f32_16x16x32_bf16 v[80:83], v[176:179], v[206:209], v[80:83]
	v_mfma_f32_16x16x32_bf16 v[68:71], v[168:171], v[214:217], v[68:71]
	v_mfma_f32_16x16x32_bf16 v[64:67], v[176:179], v[214:217], v[64:67]
	v_mfma_f32_16x16x32_bf16 v[116:119], v[172:175], v[188:191], v[116:119]
	v_mfma_f32_16x16x32_bf16 v[112:115], v[180:183], v[188:191], v[112:115]
	v_mfma_f32_16x16x32_bf16 v[100:103], v[172:175], v[202:205], v[100:103]
	v_mfma_f32_16x16x32_bf16 v[96:99], v[180:183], v[202:205], v[96:99]
	v_mfma_f32_16x16x32_bf16 v[84:87], v[172:175], v[210:213], v[84:87]
	v_mfma_f32_16x16x32_bf16 v[80:83], v[180:183], v[210:213], v[80:83]
	v_mfma_f32_16x16x32_bf16 v[68:71], v[172:175], v[228:231], v[68:71]
	v_mfma_f32_16x16x32_bf16 v[64:67], v[180:183], v[228:231], v[64:67]
	s_setprio 0
	s_barrier
	s_add_u32 s98, s12, 0x80
	s_addc_u32 s99, s13, 0
	s_add_u32 s100, s14, 0x80
	s_addc_u32 s101, s15, 0
	s_add_i32 s44, s48, s7
	s_mov_b32 m0, s44
	ds_read_b128 v[184:187], v155 offset:16384
	ds_read_b128 v[188:191], v155 offset:17408
	ds_read_b128 v[198:201], v155 offset:18432
	ds_read_b128 v[202:205], v155 offset:19456
	ds_read_b128 v[206:209], v155 offset:20480
	ds_read_b128 v[210:213], v155 offset:21504
	ds_read_b128 v[214:217], v155 offset:22528
	ds_read_b128 v[228:231], v155 offset:23552
	global_load_lds_dwordx4 v196, s[12:13]
	s_add_i32 m0, s44, 0x2000
	s_add_u32 s46, s12, 0x100000
	s_addc_u32 s47, s13, 0
	s_add_i32 s44, s90, s7
	global_load_lds_dwordx4 v132, s[12:13]
	s_mov_b32 m0, s44
	s_nop 0
	global_load_lds_dwordx4 v196, s[46:47]
	s_add_i32 m0, s44, 0x2000
	s_nop 0
	global_load_lds_dwordx4 v132, s[46:47]
	s_mov_b32 m0, s34
	s_nop 0
	global_load_lds_dwordx4 v128, s[14:15]
	s_mov_b32 m0, s35
	s_nop 0
	global_load_lds_dwordx4 v130, s[14:15]
	s_waitcnt vmcnt(8)
	s_waitcnt lgkmcnt(0)
	s_barrier
; #define PG8_STAGE(bufoff, gbase, voff) do { _Pragma("unroll") for (int _i = 0; _i < 2; ++_i) \
;         __builtin_amdgcn_global_load_lds((const unsigned*)((const char*)(gbase) + (voff)[_i]), (LAS unsigned*)(lds + (bufoff) + ldsw + _i * 8192), 16, 0, 0); } while (0)
; #define PG8_LDA(dst, b, h) do { _Pragma("unroll") for (int m = 0; m < 4; ++m) _Pragma("unroll") for (int k = 0; k < 2; ++k) dst[m][k] = *(const LAS bf16x8*)(lds + PG8_SA(b, h) + aoff + m * 2048 + k * 1024); } while (0)
; #define PG8_LDB(dst, b, h) do { _Pragma("unroll") for (int n = 0; n < 2; ++n) _Pragma("unroll") for (int k = 0; k < 2; ++k) dst[n][k] = *(const LAS bf16x8*)(lds + PG8_SB(b, h) + boff + n * 2048 + k * 1024); } while (0)
; #define PG8_MMA(ai, bj, At, Bt) do { __builtin_amdgcn_s_setprio(1); _Pragma("unroll") for (int m = 0; m < 4; ++m) _Pragma("unroll") for (int n = 0; n < 2; ++n) _Pragma("unroll") for (int k = 0; k < 2; ++k) \
;         acc[ai][bj][m][n] = __builtin_amdgcn_mfma_f32_16x16x32_bf16(Bt[n][k], At[m][k], acc[ai][bj][m][n], 0, 0, 0); __builtin_amdgcn_s_setprio(0); } while (0)
; #define PG8_WAIT_V(n) asm volatile("s_waitcnt vmcnt(" #n ")" ::: "memory")
; #define PG8_WAIT_L(n) asm volatile("s_waitcnt lgkmcnt(" #n ")" ::: "memory")
; #define PG8_BAR __builtin_amdgcn_s_barrier()
; #define PG8_SCHED __builtin_amdgcn_sched_barrier(0)
; template <class Epi, class Sched, bool ALIGN_EPI = false, bool SP2 = false>
; __device__ __forceinline__ void gemm_phase(LAS unsigned char* lds, const Gemm g, const Sched& S, const Epi& E) {
;     ...
;             PG8_WAIT_V(8); PG8_WAIT_L(0); PG8_BAR; PG8_MMA(0, 0, At, B0); PG8_MMA(0, 1, At, B1); PG8_BAR; PG8_SCHED;
;             PG8_LDA(At, 0, 1); PG8_STAGE(PG8_SB(0, 0), b2, voffB); PG8_STAGE(PG8_SB(0, 1), b2 + hstep, voffB); PG8_STAGE(PG8_SA(0, 0), a2, voffA);
;             PG8_WAIT_V(8); PG8_WAIT_L(0); PG8_BAR; PG8_MMA(1, 0, At, B0); PG8_MMA(1, 1, At, B1); PG8_BAR; PG8_SCHED;
;             PG8_LDB(B0, 1, 0); PG8_LDB(B1, 1, 1); PG8_SCHED; PG8_LDA(At, 1, 0); PG8_STAGE(PG8_SA(0, 1), a2 + hstep, voffA);
;             PG8_WAIT_V(8); PG8_WAIT_L(0); PG8_BAR; PG8_MMA(0, 0, At, B0); PG8_MMA(0, 1, At, B1); PG8_BAR; PG8_SCHED;
	s_setprio 1
	s_waitcnt lgkmcnt(0)
	v_mfma_f32_16x16x32_bf16 v[60:63], v[142:145], v[184:187], v[60:63]
	v_mfma_f32_16x16x32_bf16 v[56:59], v[160:163], v[184:187], v[56:59]
	v_mfma_f32_16x16x32_bf16 v[44:47], v[142:145], v[198:201], v[44:47]
	v_mfma_f32_16x16x32_bf16 v[40:43], v[160:163], v[198:201], v[40:43]
	v_mfma_f32_16x16x32_bf16 v[28:31], v[142:145], v[206:209], v[28:31]
	v_mfma_f32_16x16x32_bf16 v[24:27], v[160:163], v[206:209], v[24:27]
	v_mfma_f32_16x16x32_bf16 v[12:15], v[142:145], v[214:217], v[12:15]
	v_mfma_f32_16x16x32_bf16 v[8:11], v[160:163], v[214:217], v[8:11]
	v_mfma_f32_16x16x32_bf16 v[60:63], v[156:159], v[188:191], v[60:63]
	v_mfma_f32_16x16x32_bf16 v[56:59], v[164:167], v[188:191], v[56:59]
	v_mfma_f32_16x16x32_bf16 v[44:47], v[156:159], v[202:205], v[44:47]
	v_mfma_f32_16x16x32_bf16 v[40:43], v[164:167], v[202:205], v[40:43]
	v_mfma_f32_16x16x32_bf16 v[28:31], v[156:159], v[210:213], v[28:31]
	v_mfma_f32_16x16x32_bf16 v[24:27], v[164:167], v[210:213], v[24:27]
	v_mfma_f32_16x16x32_bf16 v[12:15], v[156:159], v[228:231], v[12:15]
	v_mfma_f32_16x16x32_bf16 v[8:11], v[164:167], v[228:231], v[8:11]
	s_setprio 0
	s_setprio 1
	v_mfma_f32_16x16x32_bf16 v[52:55], v[168:171], v[184:187], v[52:55]
	v_mfma_f32_16x16x32_bf16 v[48:51], v[176:179], v[184:187], v[48:51]
	v_mfma_f32_16x16x32_bf16 v[36:39], v[168:171], v[198:201], v[36:39]
	v_mfma_f32_16x16x32_bf16 v[32:35], v[176:179], v[198:201], v[32:35]
	v_mfma_f32_16x16x32_bf16 v[20:23], v[168:171], v[206:209], v[20:23]
	v_mfma_f32_16x16x32_bf16 v[16:19], v[176:179], v[206:209], v[16:19]
	v_mfma_f32_16x16x32_bf16 v[4:7], v[168:171], v[214:217], v[4:7]
	v_mfma_f32_16x16x32_bf16 v[0:3], v[176:179], v[214:217], v[0:3]
	v_mfma_f32_16x16x32_bf16 v[52:55], v[172:175], v[188:191], v[52:55]
	v_mfma_f32_16x16x32_bf16 v[48:51], v[180:183], v[188:191], v[48:51]
	v_mfma_f32_16x16x32_bf16 v[36:39], v[172:175], v[202:205], v[36:39]
	v_mfma_f32_16x16x32_bf16 v[32:35], v[180:183], v[202:205], v[32:35]
	v_mfma_f32_16x16x32_bf16 v[20:23], v[172:175], v[210:213], v[20:23]
	v_mfma_f32_16x16x32_bf16 v[16:19], v[180:183], v[210:213], v[16:19]
	v_mfma_f32_16x16x32_bf16 v[4:7], v[172:175], v[228:231], v[4:7]
	v_mfma_f32_16x16x32_bf16 v[0:3], v[180:183], v[228:231], v[0:3]
	s_setprio 0
	s_barrier
	s_add_i32 s91, 0, 0x18000
	s_add_i32 s58, 0, 0x1c000
	v_add_u32_e32 v164, s91, v149
	v_add_u32_e32 v180, s58, v149
	ds_read_b128 v[142:145], v164
	ds_read_b128 v[156:159], v164 offset:1024
	ds_read_b128 v[160:163], v164 offset:2048
	ds_read_b128 v[164:167], v164 offset:3072
	ds_read_b128 v[168:171], v180
	ds_read_b128 v[172:175], v180 offset:1024
	ds_read_b128 v[176:179], v180 offset:2048
	ds_read_b128 v[180:183], v180 offset:3072
	s_add_u32 s14, s14, 0x100000
	s_addc_u32 s15, s15, 0
	s_mov_b32 m0, s36
	ds_read_b128 v[184:187], v155 offset:32768
	ds_read_b128 v[188:191], v155 offset:33792
	ds_read_b128 v[198:201], v155 offset:34816
	ds_read_b128 v[202:205], v155 offset:35840
	ds_read_b128 v[206:209], v155 offset:36864
	ds_read_b128 v[210:213], v155 offset:37888
	ds_read_b128 v[214:217], v155 offset:38912
	ds_read_b128 v[228:231], v155 offset:39936
	global_load_lds_dwordx4 v128, s[14:15]
	s_mov_b32 m0, s37
	s_nop 0
	global_load_lds_dwordx4 v130, s[14:15]
	s_waitcnt vmcnt(8)
	s_waitcnt lgkmcnt(0)
	s_barrier
	s_setprio 1
	s_waitcnt lgkmcnt(0)
	v_mfma_f32_16x16x32_bf16 v[124:127], v[142:145], v[184:187], v[124:127]
	v_mfma_f32_16x16x32_bf16 v[120:123], v[160:163], v[184:187], v[120:123]
	v_mfma_f32_16x16x32_bf16 v[108:111], v[142:145], v[198:201], v[108:111]
	v_mfma_f32_16x16x32_bf16 v[104:107], v[160:163], v[198:201], v[104:107]
	v_mfma_f32_16x16x32_bf16 v[92:95], v[142:145], v[206:209], v[92:95]
	v_mfma_f32_16x16x32_bf16 v[88:91], v[160:163], v[206:209], v[88:91]
	v_mfma_f32_16x16x32_bf16 v[76:79], v[142:145], v[214:217], v[76:79]
	v_mfma_f32_16x16x32_bf16 v[72:75], v[160:163], v[214:217], v[72:75]
	v_mfma_f32_16x16x32_bf16 v[124:127], v[156:159], v[188:191], v[124:127]
	v_mfma_f32_16x16x32_bf16 v[120:123], v[164:167], v[188:191], v[120:123]
	v_mfma_f32_16x16x32_bf16 v[108:111], v[156:159], v[202:205], v[108:111]
	v_mfma_f32_16x16x32_bf16 v[104:107], v[164:167], v[202:205], v[104:107]
	v_mfma_f32_16x16x32_bf16 v[92:95], v[156:159], v[210:213], v[92:95]
	v_mfma_f32_16x16x32_bf16 v[88:91], v[164:167], v[210:213], v[88:91]
	v_mfma_f32_16x16x32_bf16 v[76:79], v[156:159], v[228:231], v[76:79]
	v_mfma_f32_16x16x32_bf16 v[72:75], v[164:167], v[228:231], v[72:75]
	s_setprio 0
	s_setprio 1
	v_mfma_f32_16x16x32_bf16 v[116:119], v[168:171], v[184:187], v[116:119]
	v_mfma_f32_16x16x32_bf16 v[112:115], v[176:179], v[184:187], v[112:115]
	v_mfma_f32_16x16x32_bf16 v[100:103], v[168:171], v[198:201], v[100:103]
	v_mfma_f32_16x16x32_bf16 v[96:99], v[176:179], v[198:201], v[96:99]
	v_mfma_f32_16x16x32_bf16 v[84:87], v[168:171], v[206:209], v[84:87]
	v_mfma_f32_16x16x32_bf16 v[80:83], v[176:179], v[206:209], v[80:83]
	v_mfma_f32_16x16x32_bf16 v[68:71], v[168:171], v[214:217], v[68:71]
	v_mfma_f32_16x16x32_bf16 v[64:67], v[176:179], v[214:217], v[64:67]
	v_mfma_f32_16x16x32_bf16 v[116:119], v[172:175], v[188:191], v[116:119]
	v_mfma_f32_16x16x32_bf16 v[112:115], v[180:183], v[188:191], v[112:115]
	v_mfma_f32_16x16x32_bf16 v[100:103], v[172:175], v[202:205], v[100:103]
	v_mfma_f32_16x16x32_bf16 v[96:99], v[180:183], v[202:205], v[96:99]
	v_mfma_f32_16x16x32_bf16 v[84:87], v[172:175], v[210:213], v[84:87]
	v_mfma_f32_16x16x32_bf16 v[80:83], v[180:183], v[210:213], v[80:83]
	v_mfma_f32_16x16x32_bf16 v[68:71], v[172:175], v[228:231], v[68:71]
	v_mfma_f32_16x16x32_bf16 v[64:67], v[180:183], v[228:231], v[64:67]
	s_setprio 0
	s_barrier
; #define PG8_STAGE(bufoff, gbase, voff) do { _Pragma("unroll") for (int _i = 0; _i < 2; ++_i) \
;         __builtin_amdgcn_global_load_lds((const unsigned*)((const char*)(gbase) + (voff)[_i]), (LAS unsigned*)(lds + (bufoff) + ldsw + _i * 8192), 16, 0, 0); } while (0)
; #define PG8_LDA(dst, b, h) do { _Pragma("unroll") for (int m = 0; m < 4; ++m) _Pragma("unroll") for (int k = 0; k < 2; ++k) dst[m][k] = *(const LAS bf16x8*)(lds + PG8_SA(b, h) + aoff + m * 2048 + k * 1024); } while (0)
; #define PG8_MMA(ai, bj, At, Bt) do { __builtin_amdgcn_s_setprio(1); _Pragma("unroll") for (int m = 0; m < 4; ++m) _Pragma("unroll") for (int n = 0; n < 2; ++n) _Pragma("unroll") for (int k = 0; k < 2; ++k) \
;         acc[ai][bj][m][n] = __builtin_amdgcn_mfma_f32_16x16x32_bf16(Bt[n][k], At[m][k], acc[ai][bj][m][n], 0, 0, 0); __builtin_amdgcn_s_setprio(0); } while (0)
; #define PG8_WAIT_V(n) asm volatile("s_waitcnt vmcnt(" #n ")" ::: "memory")
; #define PG8_WAIT_L(n) asm volatile("s_waitcnt lgkmcnt(" #n ")" ::: "memory")
; #define PG8_BAR __builtin_amdgcn_s_barrier()
; #define PG8_SCHED __builtin_amdgcn_sched_barrier(0)
; template <class Epi, class Sched, bool ALIGN_EPI = false, bool SP2 = false>
; __device__ __forceinline__ void gemm_phase(LAS unsigned char* lds, const Gemm g, const Sched& S, const Epi& E) {
;     ...
;             PG8_WAIT_V(8); PG8_WAIT_L(0); PG8_BAR; PG8_MMA(0, 0, At, B0); PG8_MMA(0, 1, At, B1); PG8_BAR; PG8_SCHED;
;             PG8_LDA(At, 1, 1); PG8_STAGE(PG8_SB(1, 0), b3, voffB); PG8_STAGE(PG8_SB(1, 1), b3 + hstep, voffB); PG8_STAGE(PG8_SA(1, 0), a3, voffA);
;             PG8_WAIT_V(8); PG8_WAIT_L(0); PG8_BAR; PG8_MMA(1, 0, At, B0); PG8_MMA(1, 1, At, B1); PG8_BAR; PG8_SCHED;
	s_add_i32 s14, s91, s7
	s_mov_b32 m0, s14
	ds_read_b128 v[184:187], v155 offset:49152
	ds_read_b128 v[188:191], v155 offset:50176
	ds_read_b128 v[198:201], v155 offset:51200
	ds_read_b128 v[202:205], v155 offset:52224
	ds_read_b128 v[206:209], v155 offset:53248
	ds_read_b128 v[210:213], v155 offset:54272
	ds_read_b128 v[214:217], v155 offset:55296
	ds_read_b128 v[228:231], v155 offset:56320
	global_load_lds_dwordx4 v196, s[98:99]
	s_add_i32 m0, s14, 0x2000
	s_add_u32 s12, s12, 0x100080
	s_addc_u32 s13, s13, 0
	s_add_i32 s14, s58, s7
	global_load_lds_dwordx4 v132, s[98:99]
	s_mov_b32 m0, s14
	s_nop 0
	global_load_lds_dwordx4 v196, s[12:13]
	s_add_i32 m0, s14, 0x2000
	s_nop 0
	global_load_lds_dwordx4 v132, s[12:13]
	s_mov_b32 m0, s38
	s_nop 0
	global_load_lds_dwordx4 v128, s[100:101]
	s_mov_b32 m0, s39
	s_nop 0
	global_load_lds_dwordx4 v130, s[100:101]
	s_waitcnt vmcnt(8)
	s_waitcnt lgkmcnt(0)
	s_barrier
	s_setprio 1
	s_waitcnt lgkmcnt(0)
	v_mfma_f32_16x16x32_bf16 v[60:63], v[142:145], v[184:187], v[60:63]
	v_mfma_f32_16x16x32_bf16 v[56:59], v[160:163], v[184:187], v[56:59]
	v_mfma_f32_16x16x32_bf16 v[44:47], v[142:145], v[198:201], v[44:47]
	v_mfma_f32_16x16x32_bf16 v[40:43], v[160:163], v[198:201], v[40:43]
	v_mfma_f32_16x16x32_bf16 v[28:31], v[142:145], v[206:209], v[28:31]
	v_mfma_f32_16x16x32_bf16 v[24:27], v[160:163], v[206:209], v[24:27]
	v_mfma_f32_16x16x32_bf16 v[12:15], v[142:145], v[214:217], v[12:15]
	v_mfma_f32_16x16x32_bf16 v[8:11], v[160:163], v[214:217], v[8:11]
	v_mfma_f32_16x16x32_bf16 v[60:63], v[156:159], v[188:191], v[60:63]
	v_mfma_f32_16x16x32_bf16 v[56:59], v[164:167], v[188:191], v[56:59]
	v_mfma_f32_16x16x32_bf16 v[44:47], v[156:159], v[202:205], v[44:47]
	v_mfma_f32_16x16x32_bf16 v[40:43], v[164:167], v[202:205], v[40:43]
	v_mfma_f32_16x16x32_bf16 v[28:31], v[156:159], v[210:213], v[28:31]
	v_mfma_f32_16x16x32_bf16 v[24:27], v[164:167], v[210:213], v[24:27]
	v_mfma_f32_16x16x32_bf16 v[12:15], v[156:159], v[228:231], v[12:15]
	v_mfma_f32_16x16x32_bf16 v[8:11], v[164:167], v[228:231], v[8:11]
	s_setprio 0
	s_setprio 1
	v_mfma_f32_16x16x32_bf16 v[52:55], v[168:171], v[184:187], v[52:55]
	v_mfma_f32_16x16x32_bf16 v[48:51], v[176:179], v[184:187], v[48:51]
	v_mfma_f32_16x16x32_bf16 v[36:39], v[168:171], v[198:201], v[36:39]
	v_mfma_f32_16x16x32_bf16 v[32:35], v[176:179], v[198:201], v[32:35]
	v_mfma_f32_16x16x32_bf16 v[20:23], v[168:171], v[206:209], v[20:23]
	v_mfma_f32_16x16x32_bf16 v[16:19], v[176:179], v[206:209], v[16:19]
	v_mfma_f32_16x16x32_bf16 v[4:7], v[168:171], v[214:217], v[4:7]
	v_mfma_f32_16x16x32_bf16 v[0:3], v[176:179], v[214:217], v[0:3]
	v_mfma_f32_16x16x32_bf16 v[52:55], v[172:175], v[188:191], v[52:55]
	v_mfma_f32_16x16x32_bf16 v[48:51], v[180:183], v[188:191], v[48:51]
	v_mfma_f32_16x16x32_bf16 v[36:39], v[172:175], v[202:205], v[36:39]
	v_mfma_f32_16x16x32_bf16 v[32:35], v[180:183], v[202:205], v[32:35]
	v_mfma_f32_16x16x32_bf16 v[20:23], v[172:175], v[210:213], v[20:23]
	v_mfma_f32_16x16x32_bf16 v[16:19], v[180:183], v[210:213], v[16:19]
	v_mfma_f32_16x16x32_bf16 v[4:7], v[172:175], v[228:231], v[4:7]
	v_mfma_f32_16x16x32_bf16 v[0:3], v[180:183], v[228:231], v[0:3]
	s_setprio 0
	s_barrier
	s_add_i32 s42, s42, 2
	s_add_u32 s10, s10, 0x100
	s_addc_u32 s11, s11, 0
	s_add_u32 s25, s25, 0x100
	s_addc_u32 s41, s41, 0
	s_cmp_gt_u32 s42, 61
	s_cbranch_scc0 .LBB0_424
	s_and_b64 vcc, exec, s[20:21]
	s_cbranch_vccz .LBB0_427
	s_barrier

; #define PG8_STAGE(bufoff, gbase, voff) do { _Pragma("unroll") for (int _i = 0; _i < 2; ++_i) \
;         __builtin_amdgcn_global_load_lds((const unsigned*)((const char*)(gbase) + (voff)[_i]), (LAS unsigned*)(lds + (bufoff) + ldsw + _i * 8192), 16, 0, 0); } while (0)
; #define PG8_LDA(dst, b, h) do { _Pragma("unroll") for (int m = 0; m < 4; ++m) _Pragma("unroll") for (int k = 0; k < 2; ++k) dst[m][k] = *(const LAS bf16x8*)(lds + PG8_SA(b, h) + aoff + m * 2048 + k * 1024); } while (0)
; #define PG8_LDB(dst, b, h) do { _Pragma("unroll") for (int n = 0; n < 2; ++n) _Pragma("unroll") for (int k = 0; k < 2; ++k) dst[n][k] = *(const LAS bf16x8*)(lds + PG8_SB(b, h) + boff + n * 2048 + k * 1024); } while (0)
; #define PG8_MMA(ai, bj, At, Bt) do { __builtin_amdgcn_s_setprio(1); _Pragma("unroll") for (int m = 0; m < 4; ++m) _Pragma("unroll") for (int n = 0; n < 2; ++n) _Pragma("unroll") for (int k = 0; k < 2; ++k) \
;         acc[ai][bj][m][n] = __builtin_amdgcn_mfma_f32_16x16x32_bf16(Bt[n][k], At[m][k], acc[ai][bj][m][n], 0, 0, 0); __builtin_amdgcn_s_setprio(0); } while (0)
; #define PG8_WAIT_V(n) asm volatile("s_waitcnt vmcnt(" #n ")" ::: "memory")
; #define PG8_WAIT_L(n) asm volatile("s_waitcnt lgkmcnt(" #n ")" ::: "memory")
; #define PG8_BAR __builtin_amdgcn_s_barrier()
; #define PG8_SCHED __builtin_amdgcn_sched_barrier(0)
; template <class Epi, class Sched, bool ALIGN_EPI = false, bool SP2 = false>
; __device__ __forceinline__ void gemm_phase(LAS unsigned char* lds, const Gemm g, const Sched& S, const Epi& E) {
;     ...
;             PG8_LDB(B0, 0, 0); PG8_LDB(B1, 0, 1); PG8_SCHED; PG8_LDA(At, 0, 0); PG8_STAGE(PG8_SA(1, 1), a1 + hstep, voffA);
;             PG8_WAIT_V(8); PG8_WAIT_L(0); PG8_BAR; PG8_MMA(0, 0, At, B0); PG8_MMA(0, 1, At, B1); PG8_BAR; PG8_SCHED;
;             PG8_LDA(At, 0, 1); PG8_STAGE(PG8_SB(0, 0), b2, voffB); PG8_STAGE(PG8_SB(0, 1), b2 + hstep, voffB); PG8_STAGE(PG8_SA(0, 0), a2, voffA);
;             PG8_WAIT_V(8); PG8_WAIT_L(0); PG8_BAR; PG8_MMA(1, 0, At, B0); PG8_MMA(1, 1, At, B1); PG8_BAR; PG8_SCHED;
.LBB0_510:
	v_add_u32_e32 v138, s48, v141
	ds_read_b128 v[144:147], v138
	ds_read_b128 v[148:151], v138 offset:1024
	ds_read_b128 v[152:155], v138 offset:2048
	ds_read_b128 v[156:159], v138 offset:3072
	v_add_u32_e32 v138, s90, v141
	ds_read_b128 v[160:163], v138
	ds_read_b128 v[164:167], v138 offset:1024
	ds_read_b128 v[168:171], v138 offset:2048
	ds_read_b128 v[172:175], v138 offset:3072
	s_add_u32 s26, s24, 0xfff00080
	s_addc_u32 s27, s25, -1
	s_cmp_eq_u32 s41, 60
	s_cselect_b32 s29, s19, s27
	s_cselect_b32 s28, s37, s26
	s_cselect_b32 s27, s15, s40
	s_cselect_b32 s26, s38, s39
	s_add_i32 m0, s3, 0xc000
	ds_read_b128 v[176:179], v143
	ds_read_b128 v[180:183], v143 offset:1024
	ds_read_b128 v[184:187], v143 offset:2048
	ds_read_b128 v[188:191], v143 offset:3072
	ds_read_b128 v[198:201], v143 offset:4096
	ds_read_b128 v[202:205], v143 offset:5120
	ds_read_b128 v[206:209], v143 offset:6144
	ds_read_b128 v[210:213], v143 offset:7168
	global_load_lds_dwordx4 v134, s[24:25]
	s_add_i32 m0, s3, 0xe000
	s_nop 0
	global_load_lds_dwordx4 v136, s[24:25]
	s_waitcnt vmcnt(8)
	s_waitcnt lgkmcnt(0)
	s_barrier
	s_setprio 1
	s_waitcnt lgkmcnt(0)
	v_mfma_f32_16x16x32_bf16 v[124:127], v[144:147], v[176:179], v[124:127]
	v_mfma_f32_16x16x32_bf16 v[120:123], v[152:155], v[176:179], v[120:123]
	v_mfma_f32_16x16x32_bf16 v[116:119], v[144:147], v[184:187], v[116:119]
	v_mfma_f32_16x16x32_bf16 v[108:111], v[152:155], v[184:187], v[108:111]
	v_mfma_f32_16x16x32_bf16 v[100:103], v[144:147], v[198:201], v[100:103]
	v_mfma_f32_16x16x32_bf16 v[92:95], v[152:155], v[198:201], v[92:95]
	v_mfma_f32_16x16x32_bf16 v[80:83], v[144:147], v[206:209], v[80:83]
	v_mfma_f32_16x16x32_bf16 v[72:75], v[152:155], v[206:209], v[72:75]
	v_mfma_f32_16x16x32_bf16 v[124:127], v[148:151], v[180:183], v[124:127]
	v_mfma_f32_16x16x32_bf16 v[120:123], v[156:159], v[180:183], v[120:123]
	v_mfma_f32_16x16x32_bf16 v[116:119], v[148:151], v[188:191], v[116:119]
	v_mfma_f32_16x16x32_bf16 v[108:111], v[156:159], v[188:191], v[108:111]
	v_mfma_f32_16x16x32_bf16 v[100:103], v[148:151], v[202:205], v[100:103]
	v_mfma_f32_16x16x32_bf16 v[92:95], v[156:159], v[202:205], v[92:95]
	v_mfma_f32_16x16x32_bf16 v[80:83], v[148:151], v[210:213], v[80:83]
	v_mfma_f32_16x16x32_bf16 v[72:75], v[156:159], v[210:213], v[72:75]
	s_setprio 0
	s_setprio 1
	v_mfma_f32_16x16x32_bf16 v[112:115], v[160:163], v[176:179], v[112:115]
	v_mfma_f32_16x16x32_bf16 v[104:107], v[168:171], v[176:179], v[104:107]
	v_mfma_f32_16x16x32_bf16 v[96:99], v[160:163], v[184:187], v[96:99]
	v_mfma_f32_16x16x32_bf16 v[88:91], v[168:171], v[184:187], v[88:91]
	v_mfma_f32_16x16x32_bf16 v[84:87], v[160:163], v[198:201], v[84:87]
	v_mfma_f32_16x16x32_bf16 v[76:79], v[168:171], v[198:201], v[76:79]
	v_mfma_f32_16x16x32_bf16 v[68:71], v[160:163], v[206:209], v[68:71]
	v_mfma_f32_16x16x32_bf16 v[64:67], v[168:171], v[206:209], v[64:67]
	v_mfma_f32_16x16x32_bf16 v[112:115], v[164:167], v[180:183], v[112:115]
	v_mfma_f32_16x16x32_bf16 v[104:107], v[172:175], v[180:183], v[104:107]
	v_mfma_f32_16x16x32_bf16 v[96:99], v[164:167], v[188:191], v[96:99]
	v_mfma_f32_16x16x32_bf16 v[88:91], v[172:175], v[188:191], v[88:91]
	v_mfma_f32_16x16x32_bf16 v[84:87], v[164:167], v[202:205], v[84:87]
	v_mfma_f32_16x16x32_bf16 v[76:79], v[172:175], v[202:205], v[76:79]
	v_mfma_f32_16x16x32_bf16 v[68:71], v[164:167], v[210:213], v[68:71]
	v_mfma_f32_16x16x32_bf16 v[64:67], v[172:175], v[210:213], v[64:67]
	s_setprio 0
	s_barrier
	s_add_u32 s98, s26, 0x80
	s_addc_u32 s99, s27, 0
	s_add_u32 s100, s28, 0x80
	s_addc_u32 s101, s29, 0
	s_add_i32 s42, s48, s2
	s_mov_b32 m0, s42
	ds_read_b128 v[176:179], v143 offset:16384
	ds_read_b128 v[180:183], v143 offset:17408
	ds_read_b128 v[184:187], v143 offset:18432
	ds_read_b128 v[188:191], v143 offset:19456
	ds_read_b128 v[198:201], v143 offset:20480
	ds_read_b128 v[202:205], v143 offset:21504
	ds_read_b128 v[206:209], v143 offset:22528
	ds_read_b128 v[210:213], v143 offset:23552
	global_load_lds_dwordx4 v196, s[26:27]
	s_add_i32 m0, s42, 0x2000
	s_add_u32 s46, s26, 0x100000
	s_addc_u32 s47, s27, 0
	s_add_i32 s42, s90, s2
	global_load_lds_dwordx4 v128, s[26:27]
	s_mov_b32 m0, s42
	s_nop 0
	global_load_lds_dwordx4 v196, s[46:47]
	s_add_i32 m0, s42, 0x2000
	s_nop 0
	global_load_lds_dwordx4 v128, s[46:47]
	s_mov_b32 m0, s3
	s_nop 0
	global_load_lds_dwordx4 v132, s[28:29]
	s_mov_b32 m0, s6
	s_nop 0
	global_load_lds_dwordx4 v130, s[28:29]
	s_waitcnt vmcnt(8)
	s_waitcnt lgkmcnt(0)
	s_barrier
	s_setprio 1
	s_waitcnt lgkmcnt(0)
	v_mfma_f32_16x16x32_bf16 v[60:63], v[144:147], v[176:179], v[60:63]
	v_mfma_f32_16x16x32_bf16 v[56:59], v[152:155], v[176:179], v[56:59]
	v_mfma_f32_16x16x32_bf16 v[52:55], v[144:147], v[184:187], v[52:55]
	v_mfma_f32_16x16x32_bf16 v[44:47], v[152:155], v[184:187], v[44:47]
	v_mfma_f32_16x16x32_bf16 v[36:39], v[144:147], v[198:201], v[36:39]
	v_mfma_f32_16x16x32_bf16 v[28:31], v[152:155], v[198:201], v[28:31]
	v_mfma_f32_16x16x32_bf16 v[20:23], v[144:147], v[206:209], v[20:23]
	v_mfma_f32_16x16x32_bf16 v[12:15], v[152:155], v[206:209], v[12:15]
	v_mfma_f32_16x16x32_bf16 v[60:63], v[148:151], v[180:183], v[60:63]
	v_mfma_f32_16x16x32_bf16 v[56:59], v[156:159], v[180:183], v[56:59]
	v_mfma_f32_16x16x32_bf16 v[52:55], v[148:151], v[188:191], v[52:55]
	v_mfma_f32_16x16x32_bf16 v[44:47], v[156:159], v[188:191], v[44:47]
	v_mfma_f32_16x16x32_bf16 v[36:39], v[148:151], v[202:205], v[36:39]
	v_mfma_f32_16x16x32_bf16 v[28:31], v[156:159], v[202:205], v[28:31]
	v_mfma_f32_16x16x32_bf16 v[20:23], v[148:151], v[210:213], v[20:23]
	v_mfma_f32_16x16x32_bf16 v[12:15], v[156:159], v[210:213], v[12:15]
	s_setprio 0
	s_setprio 1
	v_mfma_f32_16x16x32_bf16 v[48:51], v[160:163], v[176:179], v[48:51]
	v_mfma_f32_16x16x32_bf16 v[40:43], v[168:171], v[176:179], v[40:43]
	v_mfma_f32_16x16x32_bf16 v[32:35], v[160:163], v[184:187], v[32:35]
	v_mfma_f32_16x16x32_bf16 v[24:27], v[168:171], v[184:187], v[24:27]
	v_mfma_f32_16x16x32_bf16 v[16:19], v[160:163], v[198:201], v[16:19]
	v_mfma_f32_16x16x32_bf16 v[8:11], v[168:171], v[198:201], v[8:11]
	v_mfma_f32_16x16x32_bf16 v[4:7], v[160:163], v[206:209], v[4:7]
	v_mfma_f32_16x16x32_bf16 v[0:3], v[168:171], v[206:209], v[0:3]
	v_mfma_f32_16x16x32_bf16 v[48:51], v[164:167], v[180:183], v[48:51]
	v_mfma_f32_16x16x32_bf16 v[40:43], v[172:175], v[180:183], v[40:43]
	v_mfma_f32_16x16x32_bf16 v[32:35], v[164:167], v[188:191], v[32:35]
	v_mfma_f32_16x16x32_bf16 v[24:27], v[172:175], v[188:191], v[24:27]
	v_mfma_f32_16x16x32_bf16 v[16:19], v[164:167], v[202:205], v[16:19]
	v_mfma_f32_16x16x32_bf16 v[8:11], v[172:175], v[202:205], v[8:11]
	v_mfma_f32_16x16x32_bf16 v[4:7], v[164:167], v[210:213], v[4:7]
	v_mfma_f32_16x16x32_bf16 v[0:3], v[172:175], v[210:213], v[0:3]
	s_setprio 0
	s_barrier
; #define PG8_STAGE(bufoff, gbase, voff) do { _Pragma("unroll") for (int _i = 0; _i < 2; ++_i) \
;         __builtin_amdgcn_global_load_lds((const unsigned*)((const char*)(gbase) + (voff)[_i]), (LAS unsigned*)(lds + (bufoff) + ldsw + _i * 8192), 16, 0, 0); } while (0)
; #define PG8_LDA(dst, b, h) do { _Pragma("unroll") for (int m = 0; m < 4; ++m) _Pragma("unroll") for (int k = 0; k < 2; ++k) dst[m][k] = *(const LAS bf16x8*)(lds + PG8_SA(b, h) + aoff + m * 2048 + k * 1024); } while (0)
; #define PG8_LDB(dst, b, h) do { _Pragma("unroll") for (int n = 0; n < 2; ++n) _Pragma("unroll") for (int k = 0; k < 2; ++k) dst[n][k] = *(const LAS bf16x8*)(lds + PG8_SB(b, h) + boff + n * 2048 + k * 1024); } while (0)
; #define PG8_MMA(ai, bj, At, Bt) do { __builtin_amdgcn_s_setprio(1); _Pragma("unroll") for (int m = 0; m < 4; ++m) _Pragma("unroll") for (int n = 0; n < 2; ++n) _Pragma("unroll") for (int k = 0; k < 2; ++k) \
;         acc[ai][bj][m][n] = __builtin_amdgcn_mfma_f32_16x16x32_bf16(Bt[n][k], At[m][k], acc[ai][bj][m][n], 0, 0, 0); __builtin_amdgcn_s_setprio(0); } while (0)
; #define PG8_WAIT_V(n) asm volatile("s_waitcnt vmcnt(" #n ")" ::: "memory")
; #define PG8_WAIT_L(n) asm volatile("s_waitcnt lgkmcnt(" #n ")" ::: "memory")
; #define PG8_BAR __builtin_amdgcn_s_barrier()
; #define PG8_SCHED __builtin_amdgcn_sched_barrier(0)
; template <class Epi, class Sched, bool ALIGN_EPI = false, bool SP2 = false>
; __device__ __forceinline__ void gemm_phase(LAS unsigned char* lds, const Gemm g, const Sched& S, const Epi& E) {
;     ...
;             PG8_LDB(B0, 1, 0); PG8_LDB(B1, 1, 1); PG8_SCHED; PG8_LDA(At, 1, 0); PG8_STAGE(PG8_SA(0, 1), a2 + hstep, voffA);
;             PG8_WAIT_V(8); PG8_WAIT_L(0); PG8_BAR; PG8_MMA(0, 0, At, B0); PG8_MMA(0, 1, At, B1); PG8_BAR; PG8_SCHED;
;             PG8_LDA(At, 1, 1); PG8_STAGE(PG8_SB(1, 0), b3, voffB); PG8_STAGE(PG8_SB(1, 1), b3 + hstep, voffB); PG8_STAGE(PG8_SA(1, 0), a3, voffA);
;             PG8_WAIT_V(8); PG8_WAIT_L(0); PG8_BAR; PG8_MMA(1, 0, At, B0); PG8_MMA(1, 1, At, B1); PG8_BAR; PG8_SCHED;
	v_add_u32_e32 v156, s91, v141
	v_add_u32_e32 v172, s58, v141
	ds_read_b128 v[144:147], v156
	ds_read_b128 v[148:151], v156 offset:1024
	ds_read_b128 v[152:155], v156 offset:2048
	ds_read_b128 v[156:159], v156 offset:3072
	ds_read_b128 v[160:163], v172
	ds_read_b128 v[164:167], v172 offset:1024
	ds_read_b128 v[168:171], v172 offset:2048
	ds_read_b128 v[172:175], v172 offset:3072
	s_add_u32 s28, s28, 0x100000
	s_addc_u32 s29, s29, 0
	s_mov_b32 m0, s7
	ds_read_b128 v[176:179], v143 offset:32768
	ds_read_b128 v[180:183], v143 offset:33792
	ds_read_b128 v[184:187], v143 offset:34816
	ds_read_b128 v[188:191], v143 offset:35840
	ds_read_b128 v[198:201], v143 offset:36864
	ds_read_b128 v[202:205], v143 offset:37888
	ds_read_b128 v[206:209], v143 offset:38912
	ds_read_b128 v[210:213], v143 offset:39936
	global_load_lds_dwordx4 v132, s[28:29]
	s_mov_b32 m0, s17
	s_nop 0
	global_load_lds_dwordx4 v130, s[28:29]
	s_waitcnt vmcnt(8)
	s_waitcnt lgkmcnt(0)
	s_barrier
	s_setprio 1
	s_waitcnt lgkmcnt(0)
	v_mfma_f32_16x16x32_bf16 v[124:127], v[144:147], v[176:179], v[124:127]
	v_mfma_f32_16x16x32_bf16 v[120:123], v[152:155], v[176:179], v[120:123]
	v_mfma_f32_16x16x32_bf16 v[116:119], v[144:147], v[184:187], v[116:119]
	v_mfma_f32_16x16x32_bf16 v[108:111], v[152:155], v[184:187], v[108:111]
	v_mfma_f32_16x16x32_bf16 v[100:103], v[144:147], v[198:201], v[100:103]
	v_mfma_f32_16x16x32_bf16 v[92:95], v[152:155], v[198:201], v[92:95]
	v_mfma_f32_16x16x32_bf16 v[80:83], v[144:147], v[206:209], v[80:83]
	v_mfma_f32_16x16x32_bf16 v[72:75], v[152:155], v[206:209], v[72:75]
	v_mfma_f32_16x16x32_bf16 v[124:127], v[148:151], v[180:183], v[124:127]
	v_mfma_f32_16x16x32_bf16 v[120:123], v[156:159], v[180:183], v[120:123]
	v_mfma_f32_16x16x32_bf16 v[116:119], v[148:151], v[188:191], v[116:119]
	v_mfma_f32_16x16x32_bf16 v[108:111], v[156:159], v[188:191], v[108:111]
	v_mfma_f32_16x16x32_bf16 v[100:103], v[148:151], v[202:205], v[100:103]
	v_mfma_f32_16x16x32_bf16 v[92:95], v[156:159], v[202:205], v[92:95]
	v_mfma_f32_16x16x32_bf16 v[80:83], v[148:151], v[210:213], v[80:83]
	v_mfma_f32_16x16x32_bf16 v[72:75], v[156:159], v[210:213], v[72:75]
	s_setprio 0
	s_setprio 1
	v_mfma_f32_16x16x32_bf16 v[112:115], v[160:163], v[176:179], v[112:115]
	v_mfma_f32_16x16x32_bf16 v[104:107], v[168:171], v[176:179], v[104:107]
	v_mfma_f32_16x16x32_bf16 v[96:99], v[160:163], v[184:187], v[96:99]
	v_mfma_f32_16x16x32_bf16 v[88:91], v[168:171], v[184:187], v[88:91]
	v_mfma_f32_16x16x32_bf16 v[84:87], v[160:163], v[198:201], v[84:87]
	v_mfma_f32_16x16x32_bf16 v[76:79], v[168:171], v[198:201], v[76:79]
	v_mfma_f32_16x16x32_bf16 v[68:71], v[160:163], v[206:209], v[68:71]
	v_mfma_f32_16x16x32_bf16 v[64:67], v[168:171], v[206:209], v[64:67]
	v_mfma_f32_16x16x32_bf16 v[112:115], v[164:167], v[180:183], v[112:115]
	v_mfma_f32_16x16x32_bf16 v[104:107], v[172:175], v[180:183], v[104:107]
	v_mfma_f32_16x16x32_bf16 v[96:99], v[164:167], v[188:191], v[96:99]
	v_mfma_f32_16x16x32_bf16 v[88:91], v[172:175], v[188:191], v[88:91]
	v_mfma_f32_16x16x32_bf16 v[84:87], v[164:167], v[202:205], v[84:87]
	v_mfma_f32_16x16x32_bf16 v[76:79], v[172:175], v[202:205], v[76:79]
	v_mfma_f32_16x16x32_bf16 v[68:71], v[164:167], v[210:213], v[68:71]
	v_mfma_f32_16x16x32_bf16 v[64:67], v[172:175], v[210:213], v[64:67]
	s_setprio 0
	s_barrier
	s_add_i32 s28, s91, s2
	s_mov_b32 m0, s28
	ds_read_b128 v[176:179], v143 offset:49152
	ds_read_b128 v[180:183], v143 offset:50176
	ds_read_b128 v[184:187], v143 offset:51200
	ds_read_b128 v[188:191], v143 offset:52224
	ds_read_b128 v[198:201], v143 offset:53248
	ds_read_b128 v[202:205], v143 offset:54272
	ds_read_b128 v[206:209], v143 offset:55296
	ds_read_b128 v[210:213], v143 offset:56320
	global_load_lds_dwordx4 v196, s[98:99]
	s_add_i32 m0, s28, 0x2000
	s_add_u32 s26, s26, 0x100080
	s_addc_u32 s27, s27, 0
	s_add_i32 s28, s58, s2
	global_load_lds_dwordx4 v128, s[98:99]
	s_mov_b32 m0, s28
	s_nop 0
	global_load_lds_dwordx4 v196, s[26:27]
	s_add_i32 m0, s28, 0x2000
	s_nop 0
	global_load_lds_dwordx4 v128, s[26:27]
	s_mov_b32 m0, s30
	s_nop 0
	global_load_lds_dwordx4 v132, s[100:101]
	s_mov_b32 m0, s31
	s_nop 0
	global_load_lds_dwordx4 v130, s[100:101]
	s_waitcnt vmcnt(8)
	s_waitcnt lgkmcnt(0)
	s_barrier
	s_setprio 1
	s_waitcnt lgkmcnt(0)
	v_mfma_f32_16x16x32_bf16 v[60:63], v[144:147], v[176:179], v[60:63]
	v_mfma_f32_16x16x32_bf16 v[56:59], v[152:155], v[176:179], v[56:59]
	v_mfma_f32_16x16x32_bf16 v[52:55], v[144:147], v[184:187], v[52:55]
	v_mfma_f32_16x16x32_bf16 v[44:47], v[152:155], v[184:187], v[44:47]
	v_mfma_f32_16x16x32_bf16 v[36:39], v[144:147], v[198:201], v[36:39]
	v_mfma_f32_16x16x32_bf16 v[28:31], v[152:155], v[198:201], v[28:31]
	v_mfma_f32_16x16x32_bf16 v[20:23], v[144:147], v[206:209], v[20:23]
	v_mfma_f32_16x16x32_bf16 v[12:15], v[152:155], v[206:209], v[12:15]
	v_mfma_f32_16x16x32_bf16 v[60:63], v[148:151], v[180:183], v[60:63]
	v_mfma_f32_16x16x32_bf16 v[56:59], v[156:159], v[180:183], v[56:59]
	v_mfma_f32_16x16x32_bf16 v[52:55], v[148:151], v[188:191], v[52:55]
	v_mfma_f32_16x16x32_bf16 v[44:47], v[156:159], v[188:191], v[44:47]
	v_mfma_f32_16x16x32_bf16 v[36:39], v[148:151], v[202:205], v[36:39]
	v_mfma_f32_16x16x32_bf16 v[28:31], v[156:159], v[202:205], v[28:31]
	v_mfma_f32_16x16x32_bf16 v[20:23], v[148:151], v[210:213], v[20:23]
	v_mfma_f32_16x16x32_bf16 v[12:15], v[156:159], v[210:213], v[12:15]
	s_setprio 0
	s_setprio 1
	v_mfma_f32_16x16x32_bf16 v[48:51], v[160:163], v[176:179], v[48:51]
	v_mfma_f32_16x16x32_bf16 v[40:43], v[168:171], v[176:179], v[40:43]
	v_mfma_f32_16x16x32_bf16 v[32:35], v[160:163], v[184:187], v[32:35]
	v_mfma_f32_16x16x32_bf16 v[24:27], v[168:171], v[184:187], v[24:27]
	v_mfma_f32_16x16x32_bf16 v[16:19], v[160:163], v[198:201], v[16:19]
	v_mfma_f32_16x16x32_bf16 v[8:11], v[168:171], v[198:201], v[8:11]
	v_mfma_f32_16x16x32_bf16 v[4:7], v[160:163], v[206:209], v[4:7]
	v_mfma_f32_16x16x32_bf16 v[0:3], v[168:171], v[206:209], v[0:3]
	v_mfma_f32_16x16x32_bf16 v[48:51], v[164:167], v[180:183], v[48:51]
	v_mfma_f32_16x16x32_bf16 v[40:43], v[172:175], v[180:183], v[40:43]
	v_mfma_f32_16x16x32_bf16 v[32:35], v[164:167], v[188:191], v[32:35]
	v_mfma_f32_16x16x32_bf16 v[24:27], v[172:175], v[188:191], v[24:27]
	v_mfma_f32_16x16x32_bf16 v[16:19], v[164:167], v[202:205], v[16:19]
	v_mfma_f32_16x16x32_bf16 v[8:11], v[172:175], v[202:205], v[8:11]
	v_mfma_f32_16x16x32_bf16 v[4:7], v[164:167], v[210:213], v[4:7]
	v_mfma_f32_16x16x32_bf16 v[0:3], v[172:175], v[210:213], v[0:3]
	s_setprio 0
	s_barrier
	s_add_i32 s41, s41, 2
	s_add_u32 s24, s24, 0x100
	s_addc_u32 s25, s25, 0
	s_add_u32 s39, s39, 0x100
	s_addc_u32 s40, s40, 0
	s_cmp_gt_u32 s41, 61
	s_cbranch_scc0 .LBB0_510
	s_and_b64 vcc, exec, s[10:11]
	s_cbranch_vccz .LBB0_513
	s_barrier

; #define PG8_STAGE(bufoff, gbase, voff) do { _Pragma("unroll") for (int _i = 0; _i < 2; ++_i) \
;         __builtin_amdgcn_global_load_lds((const unsigned*)((const char*)(gbase) + (voff)[_i]), (LAS unsigned*)(lds + (bufoff) + ldsw + _i * 8192), 16, 0, 0); } while (0)
; #define PG8_LDA(dst, b, h) do { _Pragma("unroll") for (int m = 0; m < 4; ++m) _Pragma("unroll") for (int k = 0; k < 2; ++k) dst[m][k] = *(const LAS bf16x8*)(lds + PG8_SA(b, h) + aoff + m * 2048 + k * 1024); } while (0)
; #define PG8_LDB(dst, b, h) do { _Pragma("unroll") for (int n = 0; n < 2; ++n) _Pragma("unroll") for (int k = 0; k < 2; ++k) dst[n][k] = *(const LAS bf16x8*)(lds + PG8_SB(b, h) + boff + n * 2048 + k * 1024); } while (0)
; #define PG8_MMA(ai, bj, At, Bt) do { __builtin_amdgcn_s_setprio(1); _Pragma("unroll") for (int m = 0; m < 4; ++m) _Pragma("unroll") for (int n = 0; n < 2; ++n) _Pragma("unroll") for (int k = 0; k < 2; ++k) \
;         acc[ai][bj][m][n] = __builtin_amdgcn_mfma_f32_16x16x32_bf16(Bt[n][k], At[m][k], acc[ai][bj][m][n], 0, 0, 0); __builtin_amdgcn_s_setprio(0); } while (0)
; #define PG8_WAIT_V(n) asm volatile("s_waitcnt vmcnt(" #n ")" ::: "memory")
; #define PG8_WAIT_L(n) asm volatile("s_waitcnt lgkmcnt(" #n ")" ::: "memory")
; #define PG8_BAR __builtin_amdgcn_s_barrier()
; #define PG8_SCHED __builtin_amdgcn_sched_barrier(0)
; template <class Epi, class Sched, bool ALIGN_EPI = false, bool SP2 = false>
; __device__ __forceinline__ void gemm_phase(LAS unsigned char* lds, const Gemm g, const Sched& S, const Epi& E) {
;     ...
;             PG8_LDB(B0, 0, 0); PG8_LDB(B1, 0, 1); PG8_SCHED; PG8_LDA(At, 0, 0); PG8_STAGE(PG8_SA(1, 1), a1 + hstep, voffA);
;             PG8_WAIT_V(8); PG8_WAIT_L(0); PG8_BAR; PG8_MMA(0, 0, At, B0); PG8_MMA(0, 1, At, B1); PG8_BAR; PG8_SCHED;
;             PG8_LDA(At, 0, 1); PG8_STAGE(PG8_SB(0, 0), b2, voffB); PG8_STAGE(PG8_SB(0, 1), b2 + hstep, voffB); PG8_STAGE(PG8_SA(0, 0), a2, voffA);
;             PG8_WAIT_V(8); PG8_WAIT_L(0); PG8_BAR; PG8_MMA(1, 0, At, B0); PG8_MMA(1, 1, At, B1); PG8_BAR; PG8_SCHED;
.LBB0_832:
	v_add_u32_e32 v150, s48, v157
	v_add_u32_e32 v154, s90, v157
	ds_read_b128 v[128:131], v150
	ds_read_b128 v[132:135], v150 offset:1024
	ds_read_b128 v[146:149], v150 offset:2048
	ds_read_b128 v[150:153], v150 offset:3072
	ds_read_b128 v[160:163], v154
	ds_read_b128 v[164:167], v154 offset:1024
	ds_read_b128 v[168:171], v154 offset:2048
	ds_read_b128 v[172:175], v154 offset:3072
	s_add_u32 s34, s10, 0xfff00080
	s_addc_u32 s35, s11, -1
	s_cmp_eq_u32 s62, 60
	s_cselect_b32 s37, s27, s35
	s_cselect_b32 s36, s47, s34
	s_cselect_b32 s35, s25, s59
	s_cselect_b32 s34, s49, s54
	s_add_i32 m0, s3, 0xc000
	ds_read_b128 v[176:179], v159
	ds_read_b128 v[180:183], v159 offset:1024
	ds_read_b128 v[184:187], v159 offset:2048
	ds_read_b128 v[188:191], v159 offset:3072
	ds_read_b128 v[198:201], v159 offset:4096
	ds_read_b128 v[202:205], v159 offset:5120
	ds_read_b128 v[206:209], v159 offset:6144
	ds_read_b128 v[210:213], v159 offset:7168
	global_load_lds_dwordx4 v142, s[10:11]
	s_add_i32 m0, s3, 0xe000
	s_nop 0
	global_load_lds_dwordx4 v144, s[10:11]
	s_waitcnt vmcnt(8)
	s_waitcnt lgkmcnt(0)
	s_barrier
	s_setprio 1
	s_waitcnt lgkmcnt(0)
	v_mfma_f32_16x16x32_bf16 v[124:127], v[128:131], v[176:179], v[124:127]
	v_mfma_f32_16x16x32_bf16 v[120:123], v[146:149], v[176:179], v[120:123]
	v_mfma_f32_16x16x32_bf16 v[108:111], v[128:131], v[184:187], v[108:111]
	v_mfma_f32_16x16x32_bf16 v[104:107], v[146:149], v[184:187], v[104:107]
	v_mfma_f32_16x16x32_bf16 v[92:95], v[128:131], v[198:201], v[92:95]
	v_mfma_f32_16x16x32_bf16 v[88:91], v[146:149], v[198:201], v[88:91]
	v_mfma_f32_16x16x32_bf16 v[76:79], v[128:131], v[206:209], v[76:79]
	v_mfma_f32_16x16x32_bf16 v[72:75], v[146:149], v[206:209], v[72:75]
	v_mfma_f32_16x16x32_bf16 v[124:127], v[132:135], v[180:183], v[124:127]
	v_mfma_f32_16x16x32_bf16 v[120:123], v[150:153], v[180:183], v[120:123]
	v_mfma_f32_16x16x32_bf16 v[108:111], v[132:135], v[188:191], v[108:111]
	v_mfma_f32_16x16x32_bf16 v[104:107], v[150:153], v[188:191], v[104:107]
	v_mfma_f32_16x16x32_bf16 v[92:95], v[132:135], v[202:205], v[92:95]
	v_mfma_f32_16x16x32_bf16 v[88:91], v[150:153], v[202:205], v[88:91]
	v_mfma_f32_16x16x32_bf16 v[76:79], v[132:135], v[210:213], v[76:79]
	v_mfma_f32_16x16x32_bf16 v[72:75], v[150:153], v[210:213], v[72:75]
	s_setprio 0
	s_setprio 1
	v_mfma_f32_16x16x32_bf16 v[116:119], v[160:163], v[176:179], v[116:119]
	v_mfma_f32_16x16x32_bf16 v[112:115], v[168:171], v[176:179], v[112:115]
	v_mfma_f32_16x16x32_bf16 v[100:103], v[160:163], v[184:187], v[100:103]
	v_mfma_f32_16x16x32_bf16 v[96:99], v[168:171], v[184:187], v[96:99]
	v_mfma_f32_16x16x32_bf16 v[84:87], v[160:163], v[198:201], v[84:87]
	v_mfma_f32_16x16x32_bf16 v[80:83], v[168:171], v[198:201], v[80:83]
	v_mfma_f32_16x16x32_bf16 v[68:71], v[160:163], v[206:209], v[68:71]
	v_mfma_f32_16x16x32_bf16 v[64:67], v[168:171], v[206:209], v[64:67]
	v_mfma_f32_16x16x32_bf16 v[116:119], v[164:167], v[180:183], v[116:119]
	v_mfma_f32_16x16x32_bf16 v[112:115], v[172:175], v[180:183], v[112:115]
	v_mfma_f32_16x16x32_bf16 v[100:103], v[164:167], v[188:191], v[100:103]
	v_mfma_f32_16x16x32_bf16 v[96:99], v[172:175], v[188:191], v[96:99]
	v_mfma_f32_16x16x32_bf16 v[84:87], v[164:167], v[202:205], v[84:87]
	v_mfma_f32_16x16x32_bf16 v[80:83], v[172:175], v[202:205], v[80:83]
	v_mfma_f32_16x16x32_bf16 v[68:71], v[164:167], v[210:213], v[68:71]
	v_mfma_f32_16x16x32_bf16 v[64:67], v[172:175], v[210:213], v[64:67]
	s_setprio 0
	s_barrier
	s_add_u32 s98, s34, 0x80
	s_addc_u32 s99, s35, 0
	s_add_u32 s100, s36, 0x80
	s_addc_u32 s101, s37, 0
	s_add_i32 s63, s48, s0
	s_mov_b32 m0, s63
	ds_read_b128 v[176:179], v159 offset:16384
	ds_read_b128 v[180:183], v159 offset:17408
	ds_read_b128 v[184:187], v159 offset:18432
	ds_read_b128 v[188:191], v159 offset:19456
	ds_read_b128 v[198:201], v159 offset:20480
	ds_read_b128 v[202:205], v159 offset:21504
	ds_read_b128 v[206:209], v159 offset:22528
	ds_read_b128 v[210:213], v159 offset:23552
	global_load_lds_dwordx4 v196, s[34:35]
	s_add_i32 m0, s63, 0x2000
	s_add_u32 s64, s34, 0x100000
	s_addc_u32 s65, s35, 0
	s_add_i32 s63, s90, s0
	global_load_lds_dwordx4 v136, s[34:35]
	s_mov_b32 m0, s63
	s_nop 0
	global_load_lds_dwordx4 v196, s[64:65]
	s_add_i32 m0, s63, 0x2000
	s_nop 0
	global_load_lds_dwordx4 v136, s[64:65]
	s_mov_b32 m0, s3
	s_nop 0
	global_load_lds_dwordx4 v140, s[36:37]
	s_mov_b32 m0, s17
	s_nop 0
	global_load_lds_dwordx4 v138, s[36:37]
	s_waitcnt vmcnt(8)
	s_waitcnt lgkmcnt(0)
	s_barrier
	s_setprio 1
	s_waitcnt lgkmcnt(0)
	v_mfma_f32_16x16x32_bf16 v[60:63], v[128:131], v[176:179], v[60:63]
	v_mfma_f32_16x16x32_bf16 v[56:59], v[146:149], v[176:179], v[56:59]
	v_mfma_f32_16x16x32_bf16 v[44:47], v[128:131], v[184:187], v[44:47]
	v_mfma_f32_16x16x32_bf16 v[40:43], v[146:149], v[184:187], v[40:43]
	v_mfma_f32_16x16x32_bf16 v[28:31], v[128:131], v[198:201], v[28:31]
	v_mfma_f32_16x16x32_bf16 v[24:27], v[146:149], v[198:201], v[24:27]
	v_mfma_f32_16x16x32_bf16 v[12:15], v[128:131], v[206:209], v[12:15]
	v_mfma_f32_16x16x32_bf16 v[8:11], v[146:149], v[206:209], v[8:11]
	v_mfma_f32_16x16x32_bf16 v[60:63], v[132:135], v[180:183], v[60:63]
	v_mfma_f32_16x16x32_bf16 v[56:59], v[150:153], v[180:183], v[56:59]
	v_mfma_f32_16x16x32_bf16 v[44:47], v[132:135], v[188:191], v[44:47]
	v_mfma_f32_16x16x32_bf16 v[40:43], v[150:153], v[188:191], v[40:43]
	v_mfma_f32_16x16x32_bf16 v[28:31], v[132:135], v[202:205], v[28:31]
	v_mfma_f32_16x16x32_bf16 v[24:27], v[150:153], v[202:205], v[24:27]
	v_mfma_f32_16x16x32_bf16 v[12:15], v[132:135], v[210:213], v[12:15]
	v_mfma_f32_16x16x32_bf16 v[8:11], v[150:153], v[210:213], v[8:11]
	s_setprio 0
	s_setprio 1
	v_mfma_f32_16x16x32_bf16 v[52:55], v[160:163], v[176:179], v[52:55]
	v_mfma_f32_16x16x32_bf16 v[48:51], v[168:171], v[176:179], v[48:51]
	v_mfma_f32_16x16x32_bf16 v[36:39], v[160:163], v[184:187], v[36:39]
	v_mfma_f32_16x16x32_bf16 v[32:35], v[168:171], v[184:187], v[32:35]
	v_mfma_f32_16x16x32_bf16 v[20:23], v[160:163], v[198:201], v[20:23]
	v_mfma_f32_16x16x32_bf16 v[16:19], v[168:171], v[198:201], v[16:19]
	v_mfma_f32_16x16x32_bf16 v[4:7], v[160:163], v[206:209], v[4:7]
	v_mfma_f32_16x16x32_bf16 v[0:3], v[168:171], v[206:209], v[0:3]
	v_mfma_f32_16x16x32_bf16 v[52:55], v[164:167], v[180:183], v[52:55]
	v_mfma_f32_16x16x32_bf16 v[48:51], v[172:175], v[180:183], v[48:51]
	v_mfma_f32_16x16x32_bf16 v[36:39], v[164:167], v[188:191], v[36:39]
	v_mfma_f32_16x16x32_bf16 v[32:35], v[172:175], v[188:191], v[32:35]
	v_mfma_f32_16x16x32_bf16 v[20:23], v[164:167], v[202:205], v[20:23]
	v_mfma_f32_16x16x32_bf16 v[16:19], v[172:175], v[202:205], v[16:19]
	v_mfma_f32_16x16x32_bf16 v[4:7], v[164:167], v[210:213], v[4:7]
	v_mfma_f32_16x16x32_bf16 v[0:3], v[172:175], v[210:213], v[0:3]
	s_setprio 0
	s_barrier
; #define PG8_STAGE(bufoff, gbase, voff) do { _Pragma("unroll") for (int _i = 0; _i < 2; ++_i) \
;         __builtin_amdgcn_global_load_lds((const unsigned*)((const char*)(gbase) + (voff)[_i]), (LAS unsigned*)(lds + (bufoff) + ldsw + _i * 8192), 16, 0, 0); } while (0)
; #define PG8_LDA(dst, b, h) do { _Pragma("unroll") for (int m = 0; m < 4; ++m) _Pragma("unroll") for (int k = 0; k < 2; ++k) dst[m][k] = *(const LAS bf16x8*)(lds + PG8_SA(b, h) + aoff + m * 2048 + k * 1024); } while (0)
; #define PG8_LDB(dst, b, h) do { _Pragma("unroll") for (int n = 0; n < 2; ++n) _Pragma("unroll") for (int k = 0; k < 2; ++k) dst[n][k] = *(const LAS bf16x8*)(lds + PG8_SB(b, h) + boff + n * 2048 + k * 1024); } while (0)
; #define PG8_MMA(ai, bj, At, Bt) do { __builtin_amdgcn_s_setprio(1); _Pragma("unroll") for (int m = 0; m < 4; ++m) _Pragma("unroll") for (int n = 0; n < 2; ++n) _Pragma("unroll") for (int k = 0; k < 2; ++k) \
;         acc[ai][bj][m][n] = __builtin_amdgcn_mfma_f32_16x16x32_bf16(Bt[n][k], At[m][k], acc[ai][bj][m][n], 0, 0, 0); __builtin_amdgcn_s_setprio(0); } while (0)
; #define PG8_WAIT_V(n) asm volatile("s_waitcnt vmcnt(" #n ")" ::: "memory")
; #define PG8_WAIT_L(n) asm volatile("s_waitcnt lgkmcnt(" #n ")" ::: "memory")
; #define PG8_BAR __builtin_amdgcn_s_barrier()
; #define PG8_SCHED __builtin_amdgcn_sched_barrier(0)
; template <class Epi, class Sched, bool ALIGN_EPI = false, bool SP2 = false>
; __device__ __forceinline__ void gemm_phase(LAS unsigned char* lds, const Gemm g, const Sched& S, const Epi& E) {
;     ...
;             PG8_LDB(B0, 1, 0); PG8_LDB(B1, 1, 1); PG8_SCHED; PG8_LDA(At, 1, 0); PG8_STAGE(PG8_SA(0, 1), a2 + hstep, voffA);
;             PG8_WAIT_V(8); PG8_WAIT_L(0); PG8_BAR; PG8_MMA(0, 0, At, B0); PG8_MMA(0, 1, At, B1); PG8_BAR; PG8_SCHED;
;             PG8_LDA(At, 1, 1); PG8_STAGE(PG8_SB(1, 0), b3, voffB); PG8_STAGE(PG8_SB(1, 1), b3 + hstep, voffB); PG8_STAGE(PG8_SA(1, 0), a3, voffA);
;             PG8_WAIT_V(8); PG8_WAIT_L(0); PG8_BAR; PG8_MMA(1, 0, At, B0); PG8_MMA(1, 1, At, B1); PG8_BAR; PG8_SCHED;
	v_add_u32_e32 v150, s91, v157
	v_add_u32_e32 v172, s58, v157
	ds_read_b128 v[128:131], v150
	ds_read_b128 v[132:135], v150 offset:1024
	ds_read_b128 v[146:149], v150 offset:2048
	ds_read_b128 v[150:153], v150 offset:3072
	ds_read_b128 v[160:163], v172
	ds_read_b128 v[164:167], v172 offset:1024
	ds_read_b128 v[168:171], v172 offset:2048
	ds_read_b128 v[172:175], v172 offset:3072
	s_add_u32 s36, s36, 0x100000
	s_addc_u32 s37, s37, 0
	s_mov_b32 m0, s38
	ds_read_b128 v[176:179], v159 offset:32768
	ds_read_b128 v[180:183], v159 offset:33792
	ds_read_b128 v[184:187], v159 offset:34816
	ds_read_b128 v[188:191], v159 offset:35840
	ds_read_b128 v[198:201], v159 offset:36864
	ds_read_b128 v[202:205], v159 offset:37888
	ds_read_b128 v[206:209], v159 offset:38912
	ds_read_b128 v[210:213], v159 offset:39936
	global_load_lds_dwordx4 v140, s[36:37]
	s_mov_b32 m0, s39
	s_nop 0
	global_load_lds_dwordx4 v138, s[36:37]
	s_waitcnt vmcnt(8)
	s_waitcnt lgkmcnt(0)
	s_barrier
	s_setprio 1
	s_waitcnt lgkmcnt(0)
	v_mfma_f32_16x16x32_bf16 v[124:127], v[128:131], v[176:179], v[124:127]
	v_mfma_f32_16x16x32_bf16 v[120:123], v[146:149], v[176:179], v[120:123]
	v_mfma_f32_16x16x32_bf16 v[108:111], v[128:131], v[184:187], v[108:111]
	v_mfma_f32_16x16x32_bf16 v[104:107], v[146:149], v[184:187], v[104:107]
	v_mfma_f32_16x16x32_bf16 v[92:95], v[128:131], v[198:201], v[92:95]
	v_mfma_f32_16x16x32_bf16 v[88:91], v[146:149], v[198:201], v[88:91]
	v_mfma_f32_16x16x32_bf16 v[76:79], v[128:131], v[206:209], v[76:79]
	v_mfma_f32_16x16x32_bf16 v[72:75], v[146:149], v[206:209], v[72:75]
	v_mfma_f32_16x16x32_bf16 v[124:127], v[132:135], v[180:183], v[124:127]
	v_mfma_f32_16x16x32_bf16 v[120:123], v[150:153], v[180:183], v[120:123]
	v_mfma_f32_16x16x32_bf16 v[108:111], v[132:135], v[188:191], v[108:111]
	v_mfma_f32_16x16x32_bf16 v[104:107], v[150:153], v[188:191], v[104:107]
	v_mfma_f32_16x16x32_bf16 v[92:95], v[132:135], v[202:205], v[92:95]
	v_mfma_f32_16x16x32_bf16 v[88:91], v[150:153], v[202:205], v[88:91]
	v_mfma_f32_16x16x32_bf16 v[76:79], v[132:135], v[210:213], v[76:79]
	v_mfma_f32_16x16x32_bf16 v[72:75], v[150:153], v[210:213], v[72:75]
	s_setprio 0
	s_setprio 1
	v_mfma_f32_16x16x32_bf16 v[116:119], v[160:163], v[176:179], v[116:119]
	v_mfma_f32_16x16x32_bf16 v[112:115], v[168:171], v[176:179], v[112:115]
	v_mfma_f32_16x16x32_bf16 v[100:103], v[160:163], v[184:187], v[100:103]
	v_mfma_f32_16x16x32_bf16 v[96:99], v[168:171], v[184:187], v[96:99]
	v_mfma_f32_16x16x32_bf16 v[84:87], v[160:163], v[198:201], v[84:87]
	v_mfma_f32_16x16x32_bf16 v[80:83], v[168:171], v[198:201], v[80:83]
	v_mfma_f32_16x16x32_bf16 v[68:71], v[160:163], v[206:209], v[68:71]
	v_mfma_f32_16x16x32_bf16 v[64:67], v[168:171], v[206:209], v[64:67]
	v_mfma_f32_16x16x32_bf16 v[116:119], v[164:167], v[180:183], v[116:119]
	v_mfma_f32_16x16x32_bf16 v[112:115], v[172:175], v[180:183], v[112:115]
	v_mfma_f32_16x16x32_bf16 v[100:103], v[164:167], v[188:191], v[100:103]
	v_mfma_f32_16x16x32_bf16 v[96:99], v[172:175], v[188:191], v[96:99]
	v_mfma_f32_16x16x32_bf16 v[84:87], v[164:167], v[202:205], v[84:87]
	v_mfma_f32_16x16x32_bf16 v[80:83], v[172:175], v[202:205], v[80:83]
	v_mfma_f32_16x16x32_bf16 v[68:71], v[164:167], v[210:213], v[68:71]
	v_mfma_f32_16x16x32_bf16 v[64:67], v[172:175], v[210:213], v[64:67]
	s_setprio 0
	s_barrier
	s_add_i32 s36, s91, s0
	s_mov_b32 m0, s36
	ds_read_b128 v[176:179], v159 offset:49152
	ds_read_b128 v[180:183], v159 offset:50176
	ds_read_b128 v[184:187], v159 offset:51200
	ds_read_b128 v[188:191], v159 offset:52224
	ds_read_b128 v[198:201], v159 offset:53248
	ds_read_b128 v[202:205], v159 offset:54272
	ds_read_b128 v[206:209], v159 offset:55296
	ds_read_b128 v[210:213], v159 offset:56320
	global_load_lds_dwordx4 v196, s[98:99]
	s_add_i32 m0, s36, 0x2000
	s_add_u32 s34, s34, 0x100080
	s_addc_u32 s35, s35, 0
	s_add_i32 s36, s58, s0
	global_load_lds_dwordx4 v136, s[98:99]
	s_mov_b32 m0, s36
	s_nop 0
	global_load_lds_dwordx4 v196, s[34:35]
	s_add_i32 m0, s36, 0x2000
	s_nop 0
	global_load_lds_dwordx4 v136, s[34:35]
	s_mov_b32 m0, s41
	s_nop 0
	global_load_lds_dwordx4 v140, s[100:101]
	s_mov_b32 m0, s42
	s_nop 0
	global_load_lds_dwordx4 v138, s[100:101]
	s_waitcnt vmcnt(8)
	s_waitcnt lgkmcnt(0)
	s_barrier
	s_setprio 1
	s_waitcnt lgkmcnt(0)
	v_mfma_f32_16x16x32_bf16 v[60:63], v[128:131], v[176:179], v[60:63]
	v_mfma_f32_16x16x32_bf16 v[56:59], v[146:149], v[176:179], v[56:59]
	v_mfma_f32_16x16x32_bf16 v[44:47], v[128:131], v[184:187], v[44:47]
	v_mfma_f32_16x16x32_bf16 v[40:43], v[146:149], v[184:187], v[40:43]
	v_mfma_f32_16x16x32_bf16 v[28:31], v[128:131], v[198:201], v[28:31]
	v_mfma_f32_16x16x32_bf16 v[24:27], v[146:149], v[198:201], v[24:27]
	v_mfma_f32_16x16x32_bf16 v[12:15], v[128:131], v[206:209], v[12:15]
	v_mfma_f32_16x16x32_bf16 v[8:11], v[146:149], v[206:209], v[8:11]
	v_mfma_f32_16x16x32_bf16 v[60:63], v[132:135], v[180:183], v[60:63]
	v_mfma_f32_16x16x32_bf16 v[56:59], v[150:153], v[180:183], v[56:59]
	v_mfma_f32_16x16x32_bf16 v[44:47], v[132:135], v[188:191], v[44:47]
	v_mfma_f32_16x16x32_bf16 v[40:43], v[150:153], v[188:191], v[40:43]
	v_mfma_f32_16x16x32_bf16 v[28:31], v[132:135], v[202:205], v[28:31]
	v_mfma_f32_16x16x32_bf16 v[24:27], v[150:153], v[202:205], v[24:27]
	v_mfma_f32_16x16x32_bf16 v[12:15], v[132:135], v[210:213], v[12:15]
	v_mfma_f32_16x16x32_bf16 v[8:11], v[150:153], v[210:213], v[8:11]
	s_setprio 0
	s_setprio 1
	v_mfma_f32_16x16x32_bf16 v[52:55], v[160:163], v[176:179], v[52:55]
	v_mfma_f32_16x16x32_bf16 v[48:51], v[168:171], v[176:179], v[48:51]
	v_mfma_f32_16x16x32_bf16 v[36:39], v[160:163], v[184:187], v[36:39]
	v_mfma_f32_16x16x32_bf16 v[32:35], v[168:171], v[184:187], v[32:35]
	v_mfma_f32_16x16x32_bf16 v[20:23], v[160:163], v[198:201], v[20:23]
	v_mfma_f32_16x16x32_bf16 v[16:19], v[168:171], v[198:201], v[16:19]
	v_mfma_f32_16x16x32_bf16 v[4:7], v[160:163], v[206:209], v[4:7]
	v_mfma_f32_16x16x32_bf16 v[0:3], v[168:171], v[206:209], v[0:3]
	v_mfma_f32_16x16x32_bf16 v[52:55], v[164:167], v[180:183], v[52:55]
	v_mfma_f32_16x16x32_bf16 v[48:51], v[172:175], v[180:183], v[48:51]
	v_mfma_f32_16x16x32_bf16 v[36:39], v[164:167], v[188:191], v[36:39]
	v_mfma_f32_16x16x32_bf16 v[32:35], v[172:175], v[188:191], v[32:35]
	v_mfma_f32_16x16x32_bf16 v[20:23], v[164:167], v[202:205], v[20:23]
	v_mfma_f32_16x16x32_bf16 v[16:19], v[172:175], v[202:205], v[16:19]
	v_mfma_f32_16x16x32_bf16 v[4:7], v[164:167], v[210:213], v[4:7]
	v_mfma_f32_16x16x32_bf16 v[0:3], v[172:175], v[210:213], v[0:3]
	s_setprio 0
	s_barrier
	s_add_i32 s62, s62, 2
	s_add_u32 s10, s10, 0x100
	s_addc_u32 s11, s11, 0
	s_add_u32 s54, s54, 0x100
	s_addc_u32 s59, s59, 0
	s_cmp_gt_u32 s62, 61
	s_cbranch_scc0 .LBB0_832
	s_and_b64 vcc, exec, s[20:21]
	s_cbranch_vccz .LBB0_835
	s_barrier

; __global__ void __launch_bounds__(NTHREADS, 2) fwd_megakernel(Params P_) {
	.amdhsa_kernel _Z14fwd_megakernel6Params
		.amdhsa_group_segment_fixed_size 0
		.amdhsa_private_segment_fixed_size 0
		.amdhsa_kernarg_size 424
		.amdhsa_user_sgpr_count 2
		.amdhsa_user_sgpr_dispatch_ptr 0
		.amdhsa_user_sgpr_queue_ptr 0
		.amdhsa_user_sgpr_kernarg_segment_ptr 1
		.amdhsa_user_sgpr_dispatch_id 0
		.amdhsa_user_sgpr_kernarg_preload_length 0
		.amdhsa_user_sgpr_kernarg_preload_offset 0
		.amdhsa_user_sgpr_private_segment_size 0
		.amdhsa_uses_dynamic_stack 0
		.amdhsa_enable_private_segment 0
		.amdhsa_system_sgpr_workgroup_id_x 1
		.amdhsa_system_sgpr_workgroup_id_y 0
		.amdhsa_system_sgpr_workgroup_id_z 0
		.amdhsa_system_sgpr_workgroup_info 0
		.amdhsa_system_vgpr_workitem_id 2
		.amdhsa_next_free_vgpr 256
		.amdhsa_next_free_sgpr 102
		.amdhsa_accum_offset 256
		.amdhsa_reserve_vcc 1
		.amdhsa_float_round_mode_32 0
		.amdhsa_float_round_mode_16_64 0
		.amdhsa_float_denorm_mode_32 3
		.amdhsa_float_denorm_mode_16_64 3
		.amdhsa_dx10_clamp 1
		.amdhsa_ieee_mode 1
		.amdhsa_fp16_overflow 0
		.amdhsa_tg_split 0
		.amdhsa_exception_fp_ieee_invalid_op 0
		.amdhsa_exception_fp_denorm_src 0
		.amdhsa_exception_fp_ieee_div_zero 0
		.amdhsa_exception_fp_ieee_overflow 0
		.amdhsa_exception_fp_ieee_underflow 0
		.amdhsa_exception_fp_ieee_inexact 0
		.amdhsa_exception_int_div_zero 0
	.end_amdhsa_kernel

; __global__ void __launch_bounds__(NTHREADS, 2) fwd_megakernel(Params P_) {
amdhsa.kernels:
  - .agpr_count:     0
    .args:
      - .offset:         0
        .size:           168
        .value_kind:     by_value
      - .offset:         168
        .size:           4
        .value_kind:     hidden_block_count_x
      - .offset:         172
        .size:           4
        .value_kind:     hidden_block_count_y
      - .offset:         176
        .size:           4
        .value_kind:     hidden_block_count_z
      - .offset:         180
        .size:           2
        .value_kind:     hidden_group_size_x
      - .offset:         182
        .size:           2
        .value_kind:     hidden_group_size_y
      - .offset:         184
        .size:           2
        .value_kind:     hidden_group_size_z
      - .offset:         186
        .size:           2
        .value_kind:     hidden_remainder_x
      - .offset:         188
        .size:           2
        .value_kind:     hidden_remainder_y
      - .offset:         190
        .size:           2
        .value_kind:     hidden_remainder_z
      - .offset:         208
        .size:           8
        .value_kind:     hidden_global_offset_x
      - .offset:         216
        .size:           8
        .value_kind:     hidden_global_offset_y
      - .offset:         224
        .size:           8
        .value_kind:     hidden_global_offset_z
      - .offset:         232
        .size:           2
        .value_kind:     hidden_grid_dims
      - .offset:         256
        .size:           8
        .value_kind:     hidden_multigrid_sync_arg
      - .offset:         288
        .size:           4
        .value_kind:     hidden_dynamic_lds_size
    .group_segment_fixed_size: 0
    .kernarg_segment_align: 8
    .kernarg_segment_size: 424
    .language:       OpenCL C
    .language_version:
      - 2
      - 0
    .max_flat_workgroup_size: 512
    .name:           _Z14fwd_megakernel6Params
    .private_segment_fixed_size: 0
    .sgpr_count:     108
    .sgpr_spill_count: 110
    .symbol:         _Z14fwd_megakernel6Params.kd
    .uniform_work_group_size: 1
    .uses_dynamic_stack: false
    .vgpr_count:     256
    .vgpr_spill_count: 0
    .wavefront_size: 64
